# non-temporal hint on the read-once streaming loads of conv / qk_norm / v_transpose / EpiWo x rows (cache pollution); on top of the attention packed split
# baseline (speedup 1.0000x reference)
.LBB0_251:
	v_and_b32_e32 v3, 31, v7
	v_mov_b32_e32 v2, v7
	v_lshlrev_b32_e32 v4, 5, v3
	v_lshlrev_b32_e32 v3, 4, v3
	global_load_dwordx4 v[212:215], v4, s[0:1]
	global_load_dwordx4 v[216:219], v4, s[0:1] offset:16
	global_load_dwordx4 v[220:223], v4, s[0:1] offset:1024
	global_load_dwordx4 v[224:227], v4, s[0:1] offset:1040
	global_load_dwordx4 v[228:231], v4, s[0:1] offset:2048
	global_load_dwordx4 v[232:235], v4, s[0:1] offset:2064
	global_load_dwordx4 v[236:239], v4, s[4:5]
	global_load_dwordx4 v[240:243], v4, s[4:5] offset:16
	v_lshrrev_b32_e32 v38, 5, v2
	v_and_b32_e32 v39, 0x1fff, v38
	v_cmp_gt_u32_e32 vcc, 2, v39
	v_mad_u32_u24 v40, v38, s75, v3
	v_lshl_add_u32 v7, v38, 11, v3
	v_add_u32_e32 v2, s97, v2
	v_cndmask_b32_e64 v41, v205, 0, vcc
	v_cndmask_b32_e64 v6, 1.0, 0, vcc
	v_cmp_eq_u32_e32 vcc, 0, v39
	v_add_u32_e32 v41, v40, v41
	global_load_dwordx4 v[44:47], v41, s[36:37] nt
	global_load_dwordx4 v[48:51], v41, s[36:37] offset:1024 nt
	v_cndmask_b32_e64 v41, v206, 0, vcc
	v_cndmask_b32_e64 v8, 1.0, 0, vcc
	v_add_u32_e32 v41, v40, v41
	global_load_dwordx4 v[52:55], v41, s[36:37] nt
	global_load_dwordx4 v[56:59], v41, s[36:37] offset:1024 nt
	global_load_dwordx4 v[60:63], v40, s[36:37] nt
	global_load_dwordx4 v[64:67], v40, s[36:37] offset:1024 nt
	global_load_dwordx4 v[68:71], v40, s[36:37] offset:512 nt
	global_load_dwordx4 v[72:75], v40, s[36:37] offset:1536 nt
	v_lshrrev_b32_e32 v38, 5, v2
	v_and_b32_e32 v39, 0x1fff, v38
	v_cmp_gt_u32_e32 vcc, 2, v39
	v_mad_u32_u24 v40, v38, s75, v3
	v_lshl_add_u32 v11, v38, 11, v3
	v_add_u32_e32 v2, s97, v2
	v_cndmask_b32_e64 v41, v205, 0, vcc
	v_cndmask_b32_e64 v10, 1.0, 0, vcc
	v_cmp_eq_u32_e32 vcc, 0, v39
	v_add_u32_e32 v41, v40, v41
	global_load_dwordx4 v[76:79], v41, s[36:37] nt
	global_load_dwordx4 v[80:83], v41, s[36:37] offset:1024 nt
	v_cndmask_b32_e64 v41, v206, 0, vcc
	v_cndmask_b32_e64 v12, 1.0, 0, vcc
	v_add_u32_e32 v41, v40, v41
	global_load_dwordx4 v[84:87], v41, s[36:37] nt
	global_load_dwordx4 v[88:91], v41, s[36:37] offset:1024 nt
	global_load_dwordx4 v[92:95], v40, s[36:37] nt
	global_load_dwordx4 v[96:99], v40, s[36:37] offset:1024 nt
	global_load_dwordx4 v[100:103], v40, s[36:37] offset:512 nt
	global_load_dwordx4 v[104:107], v40, s[36:37] offset:1536 nt
	v_lshrrev_b32_e32 v38, 5, v2
	v_and_b32_e32 v39, 0x1fff, v38
	v_cmp_gt_u32_e32 vcc, 2, v39
	v_mad_u32_u24 v40, v38, s75, v3
	v_lshl_add_u32 v15, v38, 11, v3
	v_add_u32_e32 v2, s97, v2
	v_cndmask_b32_e64 v41, v205, 0, vcc
	v_cndmask_b32_e64 v14, 1.0, 0, vcc
	v_cmp_eq_u32_e32 vcc, 0, v39
	v_add_u32_e32 v41, v40, v41
	global_load_dwordx4 v[108:111], v41, s[36:37] nt
	global_load_dwordx4 v[112:115], v41, s[36:37] offset:1024 nt
	v_cndmask_b32_e64 v41, v206, 0, vcc
	v_cndmask_b32_e64 v16, 1.0, 0, vcc
	v_add_u32_e32 v41, v40, v41
	global_load_dwordx4 v[116:119], v41, s[36:37] nt
	global_load_dwordx4 v[120:123], v41, s[36:37] offset:1024 nt
	global_load_dwordx4 v[124:127], v40, s[36:37] nt
	global_load_dwordx4 v[128:131], v40, s[36:37] offset:1024 nt
	global_load_dwordx4 v[132:135], v40, s[36:37] offset:512 nt
	global_load_dwordx4 v[136:139], v40, s[36:37] offset:1536 nt
	v_lshrrev_b32_e32 v38, 5, v2
	v_and_b32_e32 v39, 0x1fff, v38
	v_cmp_gt_u32_e32 vcc, 2, v39
	v_mad_u32_u24 v40, v38, s75, v3
	v_lshl_add_u32 v19, v38, 11, v3
	v_add_u32_e32 v2, s97, v2
	v_cndmask_b32_e64 v41, v205, 0, vcc
	v_cndmask_b32_e64 v18, 1.0, 0, vcc
	v_cmp_eq_u32_e32 vcc, 0, v39
	v_add_u32_e32 v41, v40, v41
	global_load_dwordx4 v[162:165], v41, s[36:37] nt
	global_load_dwordx4 v[166:169], v41, s[36:37] offset:1024 nt
	v_cndmask_b32_e64 v41, v206, 0, vcc
	v_cndmask_b32_e64 v20, 1.0, 0, vcc
	v_add_u32_e32 v41, v40, v41
	global_load_dwordx4 v[170:173], v41, s[36:37] nt
	global_load_dwordx4 v[174:177], v41, s[36:37] offset:1024 nt
	global_load_dwordx4 v[178:181], v40, s[36:37] nt
	global_load_dwordx4 v[182:185], v40, s[36:37] offset:1024 nt
	global_load_dwordx4 v[186:189], v40, s[36:37] offset:512 nt
	global_load_dwordx4 v[190:193], v40, s[36:37] offset:1536 nt
	s_waitcnt vmcnt(0)
	v_lshlrev_b32_e32 v22, 16, v44
	v_and_b32_e32 v23, 0xffff0000, v44
	v_lshlrev_b32_e32 v24, 16, v45
	v_and_b32_e32 v25, 0xffff0000, v45
	v_lshlrev_b32_e32 v26, 16, v46
	v_and_b32_e32 v27, 0xffff0000, v46
	v_lshlrev_b32_e32 v28, 16, v47
	v_and_b32_e32 v29, 0xffff0000, v47
	v_lshlrev_b32_e32 v30, 16, v48
	v_and_b32_e32 v31, 0xffff0000, v48
	v_lshlrev_b32_e32 v32, 16, v49
	v_and_b32_e32 v33, 0xffff0000, v49
	v_lshlrev_b32_e32 v34, 16, v50
	v_and_b32_e32 v35, 0xffff0000, v50
	v_lshlrev_b32_e32 v36, 16, v51
	v_and_b32_e32 v37, 0xffff0000, v51
	v_pk_mul_f32 v[22:23], v[22:23], v[30:31]
	v_pk_mul_f32 v[24:25], v[24:25], v[32:33]
	v_pk_mul_f32 v[26:27], v[26:27], v[34:35]
	v_pk_mul_f32 v[28:29], v[28:29], v[36:37]
	v_pk_mul_f32 v[244:245], v[212:213], v[6:7] op_sel_hi:[1,0]
	v_pk_mul_f32 v[246:247], v[214:215], v[6:7] op_sel_hi:[1,0]
	v_pk_mul_f32 v[248:249], v[216:217], v[6:7] op_sel_hi:[1,0]
	v_pk_mul_f32 v[4:5], v[218:219], v[6:7] op_sel_hi:[1,0]
	v_pk_fma_f32 v[140:141], v[244:245], v[22:23], 0 op_sel_hi:[1,1,0]
	v_pk_fma_f32 v[142:143], v[246:247], v[24:25], 0 op_sel_hi:[1,1,0]
	v_pk_fma_f32 v[144:145], v[248:249], v[26:27], 0 op_sel_hi:[1,1,0]
	v_pk_fma_f32 v[194:195], v[4:5], v[28:29], 0 op_sel_hi:[1,1,0]
	v_lshlrev_b32_e32 v22, 16, v52
	v_and_b32_e32 v23, 0xffff0000, v52
	v_lshlrev_b32_e32 v24, 16, v53
	v_and_b32_e32 v25, 0xffff0000, v53
	v_lshlrev_b32_e32 v26, 16, v54
	v_and_b32_e32 v27, 0xffff0000, v54
	v_lshlrev_b32_e32 v28, 16, v55
	v_and_b32_e32 v29, 0xffff0000, v55
	v_lshlrev_b32_e32 v30, 16, v56
	v_and_b32_e32 v31, 0xffff0000, v56
	v_lshlrev_b32_e32 v32, 16, v57
	v_and_b32_e32 v33, 0xffff0000, v57
	v_lshlrev_b32_e32 v34, 16, v58
	v_and_b32_e32 v35, 0xffff0000, v58
	v_lshlrev_b32_e32 v36, 16, v59
	v_and_b32_e32 v37, 0xffff0000, v59
	v_pk_mul_f32 v[22:23], v[22:23], v[30:31]
	v_pk_mul_f32 v[24:25], v[24:25], v[32:33]
	v_pk_mul_f32 v[26:27], v[26:27], v[34:35]
	v_pk_mul_f32 v[28:29], v[28:29], v[36:37]
	v_pk_mul_f32 v[244:245], v[220:221], v[8:9] op_sel_hi:[1,0]
	v_pk_mul_f32 v[246:247], v[222:223], v[8:9] op_sel_hi:[1,0]
	v_pk_mul_f32 v[248:249], v[224:225], v[8:9] op_sel_hi:[1,0]
	v_pk_mul_f32 v[4:5], v[226:227], v[8:9] op_sel_hi:[1,0]
	v_pk_fma_f32 v[140:141], v[244:245], v[22:23], v[140:141]
	v_pk_fma_f32 v[142:143], v[246:247], v[24:25], v[142:143]
	v_pk_fma_f32 v[144:145], v[248:249], v[26:27], v[144:145]
	v_pk_fma_f32 v[194:195], v[4:5], v[28:29], v[194:195]
	v_lshlrev_b32_e32 v22, 16, v60
	v_and_b32_e32 v23, 0xffff0000, v60
	v_lshlrev_b32_e32 v24, 16, v61
	v_and_b32_e32 v25, 0xffff0000, v61
	v_lshlrev_b32_e32 v26, 16, v62
	v_and_b32_e32 v27, 0xffff0000, v62
	v_lshlrev_b32_e32 v28, 16, v63
	v_and_b32_e32 v29, 0xffff0000, v63
	v_lshlrev_b32_e32 v30, 16, v64
	v_and_b32_e32 v31, 0xffff0000, v64
	v_lshlrev_b32_e32 v32, 16, v65
	v_and_b32_e32 v33, 0xffff0000, v65
	v_lshlrev_b32_e32 v34, 16, v66
	v_and_b32_e32 v35, 0xffff0000, v66
	v_lshlrev_b32_e32 v36, 16, v67
	v_and_b32_e32 v37, 0xffff0000, v67
	v_pk_mul_f32 v[22:23], v[22:23], v[30:31]
	v_pk_mul_f32 v[24:25], v[24:25], v[32:33]
	v_pk_mul_f32 v[26:27], v[26:27], v[34:35]
	v_pk_mul_f32 v[28:29], v[28:29], v[36:37]
	v_pk_fma_f32 v[140:141], v[228:229], v[22:23], v[140:141]
	v_pk_fma_f32 v[142:143], v[230:231], v[24:25], v[142:143]
	v_pk_fma_f32 v[144:145], v[232:233], v[26:27], v[144:145]
	v_pk_fma_f32 v[194:195], v[234:235], v[28:29], v[194:195]
	v_pk_add_f32 v[140:141], v[236:237], v[140:141]
	v_pk_add_f32 v[142:143], v[238:239], v[142:143]
	v_pk_add_f32 v[144:145], v[240:241], v[144:145]
	v_pk_add_f32 v[194:195], v[242:243], v[194:195]
	v_lshlrev_b32_e32 v30, 16, v68
	v_and_b32_e32 v31, 0xffff0000, v68
	v_lshlrev_b32_e32 v32, 16, v69
	v_and_b32_e32 v33, 0xffff0000, v69
	v_lshlrev_b32_e32 v34, 16, v70
	v_and_b32_e32 v35, 0xffff0000, v70
	v_lshlrev_b32_e32 v36, 16, v71
	v_and_b32_e32 v37, 0xffff0000, v71
	v_lshlrev_b32_e32 v22, 16, v72
	v_and_b32_e32 v23, 0xffff0000, v72
	v_lshlrev_b32_e32 v24, 16, v73
	v_and_b32_e32 v25, 0xffff0000, v73
	v_lshlrev_b32_e32 v26, 16, v74
	v_and_b32_e32 v27, 0xffff0000, v74
	v_lshlrev_b32_e32 v28, 16, v75
	v_and_b32_e32 v29, 0xffff0000, v75
	v_pk_mul_f32 v[140:141], v[140:141], v[30:31]
	v_pk_mul_f32 v[142:143], v[142:143], v[32:33]
	v_pk_mul_f32 v[144:145], v[144:145], v[34:35]
	v_pk_mul_f32 v[194:195], v[194:195], v[36:37]
	v_mul_f32_e32 v30, 0xbfb8aa3b, v22
	v_mul_f32_e32 v31, 0xbfb8aa3b, v23
	v_mul_f32_e32 v32, 0xbfb8aa3b, v24
	v_mul_f32_e32 v33, 0xbfb8aa3b, v25
	v_mul_f32_e32 v34, 0xbfb8aa3b, v26
	v_mul_f32_e32 v35, 0xbfb8aa3b, v27
	v_mul_f32_e32 v36, 0xbfb8aa3b, v28
	v_mul_f32_e32 v37, 0xbfb8aa3b, v29
	v_exp_f32_e32 v30, v30
	v_exp_f32_e32 v31, v31
	v_exp_f32_e32 v32, v32
	v_exp_f32_e32 v33, v33
	v_exp_f32_e32 v34, v34
	v_exp_f32_e32 v35, v35
	v_exp_f32_e32 v36, v36
	v_exp_f32_e32 v37, v37
	v_add_f32_e32 v30, 1.0, v30
	v_add_f32_e32 v31, 1.0, v31
	v_add_f32_e32 v32, 1.0, v32
	v_add_f32_e32 v33, 1.0, v33
	v_add_f32_e32 v34, 1.0, v34
	v_add_f32_e32 v35, 1.0, v35
	v_add_f32_e32 v36, 1.0, v36
	v_add_f32_e32 v37, 1.0, v37
	v_rcp_f32_e32 v30, v30
	v_rcp_f32_e32 v31, v31
	v_rcp_f32_e32 v32, v32
	v_rcp_f32_e32 v33, v33
	v_rcp_f32_e32 v34, v34
	v_rcp_f32_e32 v35, v35
	v_rcp_f32_e32 v36, v36
	v_rcp_f32_e32 v37, v37
	v_pk_mul_f32 v[30:31], v[30:31], v[22:23]
	v_pk_mul_f32 v[32:33], v[32:33], v[24:25]
	v_pk_mul_f32 v[34:35], v[34:35], v[26:27]
	v_pk_mul_f32 v[36:37], v[36:37], v[28:29]
	v_pk_mul_f32 v[140:141], v[140:141], v[30:31]
	v_pk_mul_f32 v[142:143], v[142:143], v[32:33]
	v_pk_mul_f32 v[144:145], v[144:145], v[34:35]
	v_pk_mul_f32 v[194:195], v[194:195], v[36:37]
	v_cvt_pk_bf16_f32 v44, v140, v141
	v_cvt_pk_bf16_f32 v45, v142, v143
	v_cvt_pk_bf16_f32 v46, v144, v145
	v_cvt_pk_bf16_f32 v47, v194, v195
	global_store_dwordx4 v7, v[44:47], s[34:35]
	v_lshlrev_b32_e32 v22, 16, v76
	v_and_b32_e32 v23, 0xffff0000, v76
	v_lshlrev_b32_e32 v24, 16, v77
	v_and_b32_e32 v25, 0xffff0000, v77
	v_lshlrev_b32_e32 v26, 16, v78
	v_and_b32_e32 v27, 0xffff0000, v78
	v_lshlrev_b32_e32 v28, 16, v79
	v_and_b32_e32 v29, 0xffff0000, v79
	v_lshlrev_b32_e32 v30, 16, v80
	v_and_b32_e32 v31, 0xffff0000, v80
	v_lshlrev_b32_e32 v32, 16, v81
	v_and_b32_e32 v33, 0xffff0000, v81
	v_lshlrev_b32_e32 v34, 16, v82
	v_and_b32_e32 v35, 0xffff0000, v82
	v_lshlrev_b32_e32 v36, 16, v83
	v_and_b32_e32 v37, 0xffff0000, v83
	v_pk_mul_f32 v[22:23], v[22:23], v[30:31]
	v_pk_mul_f32 v[24:25], v[24:25], v[32:33]
	v_pk_mul_f32 v[26:27], v[26:27], v[34:35]
	v_pk_mul_f32 v[28:29], v[28:29], v[36:37]
	v_pk_mul_f32 v[244:245], v[212:213], v[10:11] op_sel_hi:[1,0]
	v_pk_mul_f32 v[246:247], v[214:215], v[10:11] op_sel_hi:[1,0]
	v_pk_mul_f32 v[248:249], v[216:217], v[10:11] op_sel_hi:[1,0]
	v_pk_mul_f32 v[4:5], v[218:219], v[10:11] op_sel_hi:[1,0]
	v_pk_fma_f32 v[140:141], v[244:245], v[22:23], 0 op_sel_hi:[1,1,0]
	v_pk_fma_f32 v[142:143], v[246:247], v[24:25], 0 op_sel_hi:[1,1,0]
	v_pk_fma_f32 v[144:145], v[248:249], v[26:27], 0 op_sel_hi:[1,1,0]
	v_pk_fma_f32 v[194:195], v[4:5], v[28:29], 0 op_sel_hi:[1,1,0]
	v_lshlrev_b32_e32 v22, 16, v84
	v_and_b32_e32 v23, 0xffff0000, v84
	v_lshlrev_b32_e32 v24, 16, v85
	v_and_b32_e32 v25, 0xffff0000, v85
	v_lshlrev_b32_e32 v26, 16, v86
	v_and_b32_e32 v27, 0xffff0000, v86
	v_lshlrev_b32_e32 v28, 16, v87
	v_and_b32_e32 v29, 0xffff0000, v87
	v_lshlrev_b32_e32 v30, 16, v88
	v_and_b32_e32 v31, 0xffff0000, v88
	v_lshlrev_b32_e32 v32, 16, v89
	v_and_b32_e32 v33, 0xffff0000, v89
	v_lshlrev_b32_e32 v34, 16, v90
	v_and_b32_e32 v35, 0xffff0000, v90
	v_lshlrev_b32_e32 v36, 16, v91
	v_and_b32_e32 v37, 0xffff0000, v91
	v_pk_mul_f32 v[22:23], v[22:23], v[30:31]
	v_pk_mul_f32 v[24:25], v[24:25], v[32:33]
	v_pk_mul_f32 v[26:27], v[26:27], v[34:35]
	v_pk_mul_f32 v[28:29], v[28:29], v[36:37]
	v_pk_mul_f32 v[244:245], v[220:221], v[12:13] op_sel_hi:[1,0]
	v_pk_mul_f32 v[246:247], v[222:223], v[12:13] op_sel_hi:[1,0]
	v_pk_mul_f32 v[248:249], v[224:225], v[12:13] op_sel_hi:[1,0]
	v_pk_mul_f32 v[4:5], v[226:227], v[12:13] op_sel_hi:[1,0]
	v_pk_fma_f32 v[140:141], v[244:245], v[22:23], v[140:141]
	v_pk_fma_f32 v[142:143], v[246:247], v[24:25], v[142:143]
	v_pk_fma_f32 v[144:145], v[248:249], v[26:27], v[144:145]
	v_pk_fma_f32 v[194:195], v[4:5], v[28:29], v[194:195]
	v_lshlrev_b32_e32 v22, 16, v92
	v_and_b32_e32 v23, 0xffff0000, v92
	v_lshlrev_b32_e32 v24, 16, v93
	v_and_b32_e32 v25, 0xffff0000, v93
	v_lshlrev_b32_e32 v26, 16, v94
	v_and_b32_e32 v27, 0xffff0000, v94
	v_lshlrev_b32_e32 v28, 16, v95
	v_and_b32_e32 v29, 0xffff0000, v95
	v_lshlrev_b32_e32 v30, 16, v96
	v_and_b32_e32 v31, 0xffff0000, v96
	v_lshlrev_b32_e32 v32, 16, v97
	v_and_b32_e32 v33, 0xffff0000, v97
	v_lshlrev_b32_e32 v34, 16, v98
	v_and_b32_e32 v35, 0xffff0000, v98
	v_lshlrev_b32_e32 v36, 16, v99
	v_and_b32_e32 v37, 0xffff0000, v99
	v_pk_mul_f32 v[22:23], v[22:23], v[30:31]
	v_pk_mul_f32 v[24:25], v[24:25], v[32:33]
	v_pk_mul_f32 v[26:27], v[26:27], v[34:35]
	v_pk_mul_f32 v[28:29], v[28:29], v[36:37]
	v_pk_fma_f32 v[140:141], v[228:229], v[22:23], v[140:141]
	v_pk_fma_f32 v[142:143], v[230:231], v[24:25], v[142:143]
	v_pk_fma_f32 v[144:145], v[232:233], v[26:27], v[144:145]
	v_pk_fma_f32 v[194:195], v[234:235], v[28:29], v[194:195]
	v_pk_add_f32 v[140:141], v[236:237], v[140:141]
	v_pk_add_f32 v[142:143], v[238:239], v[142:143]
	v_pk_add_f32 v[144:145], v[240:241], v[144:145]
	v_pk_add_f32 v[194:195], v[242:243], v[194:195]
	v_lshlrev_b32_e32 v30, 16, v100
	v_and_b32_e32 v31, 0xffff0000, v100
	v_lshlrev_b32_e32 v32, 16, v101
	v_and_b32_e32 v33, 0xffff0000, v101
	v_lshlrev_b32_e32 v34, 16, v102
	v_and_b32_e32 v35, 0xffff0000, v102
	v_lshlrev_b32_e32 v36, 16, v103
	v_and_b32_e32 v37, 0xffff0000, v103
	v_lshlrev_b32_e32 v22, 16, v104
	v_and_b32_e32 v23, 0xffff0000, v104
	v_lshlrev_b32_e32 v24, 16, v105
	v_and_b32_e32 v25, 0xffff0000, v105
	v_lshlrev_b32_e32 v26, 16, v106
	v_and_b32_e32 v27, 0xffff0000, v106
	v_lshlrev_b32_e32 v28, 16, v107
	v_and_b32_e32 v29, 0xffff0000, v107
	v_pk_mul_f32 v[140:141], v[140:141], v[30:31]
	v_pk_mul_f32 v[142:143], v[142:143], v[32:33]
	v_pk_mul_f32 v[144:145], v[144:145], v[34:35]
	v_pk_mul_f32 v[194:195], v[194:195], v[36:37]
	v_mul_f32_e32 v30, 0xbfb8aa3b, v22
	v_mul_f32_e32 v31, 0xbfb8aa3b, v23
	v_mul_f32_e32 v32, 0xbfb8aa3b, v24
	v_mul_f32_e32 v33, 0xbfb8aa3b, v25
	v_mul_f32_e32 v34, 0xbfb8aa3b, v26
	v_mul_f32_e32 v35, 0xbfb8aa3b, v27
	v_mul_f32_e32 v36, 0xbfb8aa3b, v28
	v_mul_f32_e32 v37, 0xbfb8aa3b, v29
	v_exp_f32_e32 v30, v30
	v_exp_f32_e32 v31, v31
	v_exp_f32_e32 v32, v32
	v_exp_f32_e32 v33, v33
	v_exp_f32_e32 v34, v34
	v_exp_f32_e32 v35, v35
	v_exp_f32_e32 v36, v36
	v_exp_f32_e32 v37, v37
	v_add_f32_e32 v30, 1.0, v30
	v_add_f32_e32 v31, 1.0, v31
	v_add_f32_e32 v32, 1.0, v32
	v_add_f32_e32 v33, 1.0, v33
	v_add_f32_e32 v34, 1.0, v34
	v_add_f32_e32 v35, 1.0, v35
	v_add_f32_e32 v36, 1.0, v36
	v_add_f32_e32 v37, 1.0, v37
	v_rcp_f32_e32 v30, v30
	v_rcp_f32_e32 v31, v31
	v_rcp_f32_e32 v32, v32
	v_rcp_f32_e32 v33, v33
	v_rcp_f32_e32 v34, v34
	v_rcp_f32_e32 v35, v35
	v_rcp_f32_e32 v36, v36
	v_rcp_f32_e32 v37, v37
	v_pk_mul_f32 v[30:31], v[30:31], v[22:23]
	v_pk_mul_f32 v[32:33], v[32:33], v[24:25]
	v_pk_mul_f32 v[34:35], v[34:35], v[26:27]
	v_pk_mul_f32 v[36:37], v[36:37], v[28:29]
	v_pk_mul_f32 v[140:141], v[140:141], v[30:31]
	v_pk_mul_f32 v[142:143], v[142:143], v[32:33]
	v_pk_mul_f32 v[144:145], v[144:145], v[34:35]
	v_pk_mul_f32 v[194:195], v[194:195], v[36:37]
	v_cvt_pk_bf16_f32 v76, v140, v141
	v_cvt_pk_bf16_f32 v77, v142, v143
	v_cvt_pk_bf16_f32 v78, v144, v145
	v_cvt_pk_bf16_f32 v79, v194, v195
	global_store_dwordx4 v11, v[76:79], s[34:35]
	v_lshlrev_b32_e32 v22, 16, v108
	v_and_b32_e32 v23, 0xffff0000, v108
	v_lshlrev_b32_e32 v24, 16, v109
	v_and_b32_e32 v25, 0xffff0000, v109
	v_lshlrev_b32_e32 v26, 16, v110
	v_and_b32_e32 v27, 0xffff0000, v110
	v_lshlrev_b32_e32 v28, 16, v111
	v_and_b32_e32 v29, 0xffff0000, v111
	v_lshlrev_b32_e32 v30, 16, v112
	v_and_b32_e32 v31, 0xffff0000, v112
	v_lshlrev_b32_e32 v32, 16, v113
	v_and_b32_e32 v33, 0xffff0000, v113
	v_lshlrev_b32_e32 v34, 16, v114
	v_and_b32_e32 v35, 0xffff0000, v114
	v_lshlrev_b32_e32 v36, 16, v115
	v_and_b32_e32 v37, 0xffff0000, v115
	v_pk_mul_f32 v[22:23], v[22:23], v[30:31]
	v_pk_mul_f32 v[24:25], v[24:25], v[32:33]
	v_pk_mul_f32 v[26:27], v[26:27], v[34:35]
	v_pk_mul_f32 v[28:29], v[28:29], v[36:37]
	v_pk_mul_f32 v[244:245], v[212:213], v[14:15] op_sel_hi:[1,0]
	v_pk_mul_f32 v[246:247], v[214:215], v[14:15] op_sel_hi:[1,0]
	v_pk_mul_f32 v[248:249], v[216:217], v[14:15] op_sel_hi:[1,0]
	v_pk_mul_f32 v[4:5], v[218:219], v[14:15] op_sel_hi:[1,0]
	v_pk_fma_f32 v[140:141], v[244:245], v[22:23], 0 op_sel_hi:[1,1,0]
	v_pk_fma_f32 v[142:143], v[246:247], v[24:25], 0 op_sel_hi:[1,1,0]
	v_pk_fma_f32 v[144:145], v[248:249], v[26:27], 0 op_sel_hi:[1,1,0]
	v_pk_fma_f32 v[194:195], v[4:5], v[28:29], 0 op_sel_hi:[1,1,0]
	v_lshlrev_b32_e32 v22, 16, v116
	v_and_b32_e32 v23, 0xffff0000, v116
	v_lshlrev_b32_e32 v24, 16, v117
	v_and_b32_e32 v25, 0xffff0000, v117
	v_lshlrev_b32_e32 v26, 16, v118
	v_and_b32_e32 v27, 0xffff0000, v118
	v_lshlrev_b32_e32 v28, 16, v119
	v_and_b32_e32 v29, 0xffff0000, v119
	v_lshlrev_b32_e32 v30, 16, v120
	v_and_b32_e32 v31, 0xffff0000, v120
	v_lshlrev_b32_e32 v32, 16, v121
	v_and_b32_e32 v33, 0xffff0000, v121
	v_lshlrev_b32_e32 v34, 16, v122
	v_and_b32_e32 v35, 0xffff0000, v122
	v_lshlrev_b32_e32 v36, 16, v123
	v_and_b32_e32 v37, 0xffff0000, v123
	v_pk_mul_f32 v[22:23], v[22:23], v[30:31]
	v_pk_mul_f32 v[24:25], v[24:25], v[32:33]
	v_pk_mul_f32 v[26:27], v[26:27], v[34:35]
	v_pk_mul_f32 v[28:29], v[28:29], v[36:37]
	v_pk_mul_f32 v[244:245], v[220:221], v[16:17] op_sel_hi:[1,0]
	v_pk_mul_f32 v[246:247], v[222:223], v[16:17] op_sel_hi:[1,0]
	v_pk_mul_f32 v[248:249], v[224:225], v[16:17] op_sel_hi:[1,0]
	v_pk_mul_f32 v[4:5], v[226:227], v[16:17] op_sel_hi:[1,0]
	v_pk_fma_f32 v[140:141], v[244:245], v[22:23], v[140:141]
	v_pk_fma_f32 v[142:143], v[246:247], v[24:25], v[142:143]
	v_pk_fma_f32 v[144:145], v[248:249], v[26:27], v[144:145]
	v_pk_fma_f32 v[194:195], v[4:5], v[28:29], v[194:195]
	v_lshlrev_b32_e32 v22, 16, v124
	v_and_b32_e32 v23, 0xffff0000, v124
	v_lshlrev_b32_e32 v24, 16, v125
	v_and_b32_e32 v25, 0xffff0000, v125
	v_lshlrev_b32_e32 v26, 16, v126
	v_and_b32_e32 v27, 0xffff0000, v126
	v_lshlrev_b32_e32 v28, 16, v127
	v_and_b32_e32 v29, 0xffff0000, v127
	v_lshlrev_b32_e32 v30, 16, v128
	v_and_b32_e32 v31, 0xffff0000, v128
	v_lshlrev_b32_e32 v32, 16, v129
	v_and_b32_e32 v33, 0xffff0000, v129
	v_lshlrev_b32_e32 v34, 16, v130
	v_and_b32_e32 v35, 0xffff0000, v130
	v_lshlrev_b32_e32 v36, 16, v131
	v_and_b32_e32 v37, 0xffff0000, v131
	v_pk_mul_f32 v[22:23], v[22:23], v[30:31]
	v_pk_mul_f32 v[24:25], v[24:25], v[32:33]
	v_pk_mul_f32 v[26:27], v[26:27], v[34:35]
	v_pk_mul_f32 v[28:29], v[28:29], v[36:37]
	v_pk_fma_f32 v[140:141], v[228:229], v[22:23], v[140:141]
	v_pk_fma_f32 v[142:143], v[230:231], v[24:25], v[142:143]
	v_pk_fma_f32 v[144:145], v[232:233], v[26:27], v[144:145]
	v_pk_fma_f32 v[194:195], v[234:235], v[28:29], v[194:195]
	v_pk_add_f32 v[140:141], v[236:237], v[140:141]
	v_pk_add_f32 v[142:143], v[238:239], v[142:143]
	v_pk_add_f32 v[144:145], v[240:241], v[144:145]
	v_pk_add_f32 v[194:195], v[242:243], v[194:195]
	v_lshlrev_b32_e32 v30, 16, v132
	v_and_b32_e32 v31, 0xffff0000, v132
	v_lshlrev_b32_e32 v32, 16, v133
	v_and_b32_e32 v33, 0xffff0000, v133
	v_lshlrev_b32_e32 v34, 16, v134
	v_and_b32_e32 v35, 0xffff0000, v134
	v_lshlrev_b32_e32 v36, 16, v135
	v_and_b32_e32 v37, 0xffff0000, v135
	v_lshlrev_b32_e32 v22, 16, v136
	v_and_b32_e32 v23, 0xffff0000, v136
	v_lshlrev_b32_e32 v24, 16, v137
	v_and_b32_e32 v25, 0xffff0000, v137
	v_lshlrev_b32_e32 v26, 16, v138
	v_and_b32_e32 v27, 0xffff0000, v138
	v_lshlrev_b32_e32 v28, 16, v139
	v_and_b32_e32 v29, 0xffff0000, v139
	v_pk_mul_f32 v[140:141], v[140:141], v[30:31]
	v_pk_mul_f32 v[142:143], v[142:143], v[32:33]
	v_pk_mul_f32 v[144:145], v[144:145], v[34:35]
	v_pk_mul_f32 v[194:195], v[194:195], v[36:37]
	v_mul_f32_e32 v30, 0xbfb8aa3b, v22
	v_mul_f32_e32 v31, 0xbfb8aa3b, v23
	v_mul_f32_e32 v32, 0xbfb8aa3b, v24
	v_mul_f32_e32 v33, 0xbfb8aa3b, v25
	v_mul_f32_e32 v34, 0xbfb8aa3b, v26
	v_mul_f32_e32 v35, 0xbfb8aa3b, v27
	v_mul_f32_e32 v36, 0xbfb8aa3b, v28
	v_mul_f32_e32 v37, 0xbfb8aa3b, v29
	v_exp_f32_e32 v30, v30
	v_exp_f32_e32 v31, v31
	v_exp_f32_e32 v32, v32
	v_exp_f32_e32 v33, v33
	v_exp_f32_e32 v34, v34
	v_exp_f32_e32 v35, v35
	v_exp_f32_e32 v36, v36
	v_exp_f32_e32 v37, v37
	v_add_f32_e32 v30, 1.0, v30
	v_add_f32_e32 v31, 1.0, v31
	v_add_f32_e32 v32, 1.0, v32
	v_add_f32_e32 v33, 1.0, v33
	v_add_f32_e32 v34, 1.0, v34
	v_add_f32_e32 v35, 1.0, v35
	v_add_f32_e32 v36, 1.0, v36
	v_add_f32_e32 v37, 1.0, v37
	v_rcp_f32_e32 v30, v30
	v_rcp_f32_e32 v31, v31
	v_rcp_f32_e32 v32, v32
	v_rcp_f32_e32 v33, v33
	v_rcp_f32_e32 v34, v34
	v_rcp_f32_e32 v35, v35
	v_rcp_f32_e32 v36, v36
	v_rcp_f32_e32 v37, v37
	v_pk_mul_f32 v[30:31], v[30:31], v[22:23]
	v_pk_mul_f32 v[32:33], v[32:33], v[24:25]
	v_pk_mul_f32 v[34:35], v[34:35], v[26:27]
	v_pk_mul_f32 v[36:37], v[36:37], v[28:29]
	v_pk_mul_f32 v[140:141], v[140:141], v[30:31]
	v_pk_mul_f32 v[142:143], v[142:143], v[32:33]
	v_pk_mul_f32 v[144:145], v[144:145], v[34:35]
	v_pk_mul_f32 v[194:195], v[194:195], v[36:37]
	v_cvt_pk_bf16_f32 v108, v140, v141
	v_cvt_pk_bf16_f32 v109, v142, v143
	v_cvt_pk_bf16_f32 v110, v144, v145
	v_cvt_pk_bf16_f32 v111, v194, v195
	global_store_dwordx4 v15, v[108:111], s[34:35]
	v_lshlrev_b32_e32 v22, 16, v162
	v_and_b32_e32 v23, 0xffff0000, v162
	v_lshlrev_b32_e32 v24, 16, v163
	v_and_b32_e32 v25, 0xffff0000, v163
	v_lshlrev_b32_e32 v26, 16, v164
	v_and_b32_e32 v27, 0xffff0000, v164
	v_lshlrev_b32_e32 v28, 16, v165
	v_and_b32_e32 v29, 0xffff0000, v165
	v_lshlrev_b32_e32 v30, 16, v166
	v_and_b32_e32 v31, 0xffff0000, v166
	v_lshlrev_b32_e32 v32, 16, v167
	v_and_b32_e32 v33, 0xffff0000, v167
	v_lshlrev_b32_e32 v34, 16, v168
	v_and_b32_e32 v35, 0xffff0000, v168
	v_lshlrev_b32_e32 v36, 16, v169
	v_and_b32_e32 v37, 0xffff0000, v169
	v_pk_mul_f32 v[22:23], v[22:23], v[30:31]
	v_pk_mul_f32 v[24:25], v[24:25], v[32:33]
	v_pk_mul_f32 v[26:27], v[26:27], v[34:35]
	v_pk_mul_f32 v[28:29], v[28:29], v[36:37]
	v_pk_mul_f32 v[244:245], v[212:213], v[18:19] op_sel_hi:[1,0]
	v_pk_mul_f32 v[246:247], v[214:215], v[18:19] op_sel_hi:[1,0]
	v_pk_mul_f32 v[248:249], v[216:217], v[18:19] op_sel_hi:[1,0]
	v_pk_mul_f32 v[4:5], v[218:219], v[18:19] op_sel_hi:[1,0]
	v_pk_fma_f32 v[140:141], v[244:245], v[22:23], 0 op_sel_hi:[1,1,0]
	v_pk_fma_f32 v[142:143], v[246:247], v[24:25], 0 op_sel_hi:[1,1,0]
	v_pk_fma_f32 v[144:145], v[248:249], v[26:27], 0 op_sel_hi:[1,1,0]
	v_pk_fma_f32 v[194:195], v[4:5], v[28:29], 0 op_sel_hi:[1,1,0]
	v_lshlrev_b32_e32 v22, 16, v170
	v_and_b32_e32 v23, 0xffff0000, v170
	v_lshlrev_b32_e32 v24, 16, v171
	v_and_b32_e32 v25, 0xffff0000, v171
	v_lshlrev_b32_e32 v26, 16, v172
	v_and_b32_e32 v27, 0xffff0000, v172
	v_lshlrev_b32_e32 v28, 16, v173
	v_and_b32_e32 v29, 0xffff0000, v173
	v_lshlrev_b32_e32 v30, 16, v174
	v_and_b32_e32 v31, 0xffff0000, v174
	v_lshlrev_b32_e32 v32, 16, v175
	v_and_b32_e32 v33, 0xffff0000, v175
	v_lshlrev_b32_e32 v34, 16, v176
	v_and_b32_e32 v35, 0xffff0000, v176
	v_lshlrev_b32_e32 v36, 16, v177
	v_and_b32_e32 v37, 0xffff0000, v177
	v_pk_mul_f32 v[22:23], v[22:23], v[30:31]
	v_pk_mul_f32 v[24:25], v[24:25], v[32:33]
	v_pk_mul_f32 v[26:27], v[26:27], v[34:35]
	v_pk_mul_f32 v[28:29], v[28:29], v[36:37]
	v_pk_mul_f32 v[244:245], v[220:221], v[20:21] op_sel_hi:[1,0]
	v_pk_mul_f32 v[246:247], v[222:223], v[20:21] op_sel_hi:[1,0]
	v_pk_mul_f32 v[248:249], v[224:225], v[20:21] op_sel_hi:[1,0]
	v_pk_mul_f32 v[4:5], v[226:227], v[20:21] op_sel_hi:[1,0]
	v_pk_fma_f32 v[140:141], v[244:245], v[22:23], v[140:141]
	v_pk_fma_f32 v[142:143], v[246:247], v[24:25], v[142:143]
	v_pk_fma_f32 v[144:145], v[248:249], v[26:27], v[144:145]
	v_pk_fma_f32 v[194:195], v[4:5], v[28:29], v[194:195]
	v_lshlrev_b32_e32 v22, 16, v178
	v_and_b32_e32 v23, 0xffff0000, v178
	v_lshlrev_b32_e32 v24, 16, v179
	v_and_b32_e32 v25, 0xffff0000, v179
	v_lshlrev_b32_e32 v26, 16, v180
	v_and_b32_e32 v27, 0xffff0000, v180
	v_lshlrev_b32_e32 v28, 16, v181
	v_and_b32_e32 v29, 0xffff0000, v181
	v_lshlrev_b32_e32 v30, 16, v182
	v_and_b32_e32 v31, 0xffff0000, v182
	v_lshlrev_b32_e32 v32, 16, v183
	v_and_b32_e32 v33, 0xffff0000, v183
	v_lshlrev_b32_e32 v34, 16, v184
	v_and_b32_e32 v35, 0xffff0000, v184
	v_lshlrev_b32_e32 v36, 16, v185
	v_and_b32_e32 v37, 0xffff0000, v185
	v_pk_mul_f32 v[22:23], v[22:23], v[30:31]
	v_pk_mul_f32 v[24:25], v[24:25], v[32:33]
	v_pk_mul_f32 v[26:27], v[26:27], v[34:35]
	v_pk_mul_f32 v[28:29], v[28:29], v[36:37]
	v_pk_fma_f32 v[140:141], v[228:229], v[22:23], v[140:141]
	v_pk_fma_f32 v[142:143], v[230:231], v[24:25], v[142:143]
	v_pk_fma_f32 v[144:145], v[232:233], v[26:27], v[144:145]
	v_pk_fma_f32 v[194:195], v[234:235], v[28:29], v[194:195]
	v_pk_add_f32 v[140:141], v[236:237], v[140:141]
	v_pk_add_f32 v[142:143], v[238:239], v[142:143]
	v_pk_add_f32 v[144:145], v[240:241], v[144:145]
	v_pk_add_f32 v[194:195], v[242:243], v[194:195]
	v_lshlrev_b32_e32 v30, 16, v186
	v_and_b32_e32 v31, 0xffff0000, v186
	v_lshlrev_b32_e32 v32, 16, v187
	v_and_b32_e32 v33, 0xffff0000, v187
	v_lshlrev_b32_e32 v34, 16, v188
	v_and_b32_e32 v35, 0xffff0000, v188
	v_lshlrev_b32_e32 v36, 16, v189
	v_and_b32_e32 v37, 0xffff0000, v189
	v_lshlrev_b32_e32 v22, 16, v190
	v_and_b32_e32 v23, 0xffff0000, v190
	v_lshlrev_b32_e32 v24, 16, v191
	v_and_b32_e32 v25, 0xffff0000, v191
	v_lshlrev_b32_e32 v26, 16, v192
	v_and_b32_e32 v27, 0xffff0000, v192
	v_lshlrev_b32_e32 v28, 16, v193
	v_and_b32_e32 v29, 0xffff0000, v193
	v_pk_mul_f32 v[140:141], v[140:141], v[30:31]
	v_pk_mul_f32 v[142:143], v[142:143], v[32:33]
	v_pk_mul_f32 v[144:145], v[144:145], v[34:35]
	v_pk_mul_f32 v[194:195], v[194:195], v[36:37]
	v_mul_f32_e32 v30, 0xbfb8aa3b, v22
	v_mul_f32_e32 v31, 0xbfb8aa3b, v23
	v_mul_f32_e32 v32, 0xbfb8aa3b, v24
	v_mul_f32_e32 v33, 0xbfb8aa3b, v25
	v_mul_f32_e32 v34, 0xbfb8aa3b, v26
	v_mul_f32_e32 v35, 0xbfb8aa3b, v27
	v_mul_f32_e32 v36, 0xbfb8aa3b, v28
	v_mul_f32_e32 v37, 0xbfb8aa3b, v29
	v_exp_f32_e32 v30, v30
	v_exp_f32_e32 v31, v31
	v_exp_f32_e32 v32, v32
	v_exp_f32_e32 v33, v33
	v_exp_f32_e32 v34, v34
	v_exp_f32_e32 v35, v35
	v_exp_f32_e32 v36, v36
	v_exp_f32_e32 v37, v37
	v_add_f32_e32 v30, 1.0, v30
	v_add_f32_e32 v31, 1.0, v31
	v_add_f32_e32 v32, 1.0, v32
	v_add_f32_e32 v33, 1.0, v33
	v_add_f32_e32 v34, 1.0, v34
	v_add_f32_e32 v35, 1.0, v35
	v_add_f32_e32 v36, 1.0, v36
	v_add_f32_e32 v37, 1.0, v37
	v_rcp_f32_e32 v30, v30
	v_rcp_f32_e32 v31, v31
	v_rcp_f32_e32 v32, v32
	v_rcp_f32_e32 v33, v33
	v_rcp_f32_e32 v34, v34
	v_rcp_f32_e32 v35, v35
	v_rcp_f32_e32 v36, v36
	v_rcp_f32_e32 v37, v37
	v_pk_mul_f32 v[30:31], v[30:31], v[22:23]
	v_pk_mul_f32 v[32:33], v[32:33], v[24:25]
	v_pk_mul_f32 v[34:35], v[34:35], v[26:27]
	v_pk_mul_f32 v[36:37], v[36:37], v[28:29]
	v_pk_mul_f32 v[140:141], v[140:141], v[30:31]
	v_pk_mul_f32 v[142:143], v[142:143], v[32:33]
	v_pk_mul_f32 v[144:145], v[144:145], v[34:35]
	v_pk_mul_f32 v[194:195], v[194:195], v[36:37]
	v_cvt_pk_bf16_f32 v162, v140, v141
	v_cvt_pk_bf16_f32 v163, v142, v143
	v_cvt_pk_bf16_f32 v164, v144, v145
	v_cvt_pk_bf16_f32 v165, v194, v195
	global_store_dwordx4 v19, v[162:165], s[34:35]
	s_waitcnt vmcnt(0)
	v_lshrrev_b32_e32 v38, 5, v2
	v_and_b32_e32 v39, 0x1fff, v38
	v_cmp_gt_u32_e32 vcc, 2, v39
	v_mad_u32_u24 v40, v38, s75, v3
	v_lshl_add_u32 v42, v38, 11, v3
	v_add_u32_e32 v2, s97, v2
	v_cndmask_b32_e64 v41, v205, 0, vcc
	v_cndmask_b32_e64 v6, 1.0, 0, vcc
	v_cmp_eq_u32_e32 vcc, 0, v39
	v_add_u32_e32 v41, v40, v41
	global_load_dwordx4 v[44:47], v41, s[36:37] nt
	global_load_dwordx4 v[48:51], v41, s[36:37] offset:1024 nt
	v_cndmask_b32_e64 v41, v206, 0, vcc
	v_cndmask_b32_e64 v8, 1.0, 0, vcc
	v_add_u32_e32 v41, v40, v41
	global_load_dwordx4 v[52:55], v41, s[36:37] nt
	global_load_dwordx4 v[56:59], v41, s[36:37] offset:1024 nt
	global_load_dwordx4 v[60:63], v40, s[36:37] nt
	global_load_dwordx4 v[64:67], v40, s[36:37] offset:1024 nt
	global_load_dwordx4 v[68:71], v40, s[36:37] offset:512 nt
	global_load_dwordx4 v[72:75], v40, s[36:37] offset:1536 nt
	v_lshrrev_b32_e32 v38, 5, v2
	v_and_b32_e32 v39, 0x1fff, v38
	v_cmp_gt_u32_e32 vcc, 2, v39
	v_mad_u32_u24 v40, v38, s75, v3
	v_lshl_add_u32 v9, v38, 11, v3
	v_add_u32_e32 v2, s97, v2
	v_cndmask_b32_e64 v41, v205, 0, vcc
	v_cndmask_b32_e64 v10, 1.0, 0, vcc
	v_cmp_eq_u32_e32 vcc, 0, v39
	v_add_u32_e32 v41, v40, v41
	global_load_dwordx4 v[76:79], v41, s[36:37] nt
	global_load_dwordx4 v[80:83], v41, s[36:37] offset:1024 nt
	v_cndmask_b32_e64 v41, v206, 0, vcc
	v_cndmask_b32_e64 v12, 1.0, 0, vcc
	v_add_u32_e32 v41, v40, v41
	global_load_dwordx4 v[84:87], v41, s[36:37] nt
	global_load_dwordx4 v[88:91], v41, s[36:37] offset:1024 nt
	global_load_dwordx4 v[92:95], v40, s[36:37] nt
	global_load_dwordx4 v[96:99], v40, s[36:37] offset:1024 nt
	global_load_dwordx4 v[100:103], v40, s[36:37] offset:512 nt
	global_load_dwordx4 v[104:107], v40, s[36:37] offset:1536 nt
	v_lshrrev_b32_e32 v38, 5, v2
	v_and_b32_e32 v39, 0x1fff, v38
	v_cmp_gt_u32_e32 vcc, 2, v39
	v_mad_u32_u24 v40, v38, s75, v3
	v_lshl_add_u32 v13, v38, 11, v3
	v_add_u32_e32 v2, s97, v2
	v_cndmask_b32_e64 v41, v205, 0, vcc
	v_cndmask_b32_e64 v14, 1.0, 0, vcc
	v_cmp_eq_u32_e32 vcc, 0, v39
	v_add_u32_e32 v41, v40, v41
	global_load_dwordx4 v[108:111], v41, s[36:37] nt
	global_load_dwordx4 v[112:115], v41, s[36:37] offset:1024 nt
	v_cndmask_b32_e64 v41, v206, 0, vcc
	v_cndmask_b32_e64 v16, 1.0, 0, vcc
	v_add_u32_e32 v41, v40, v41
	global_load_dwordx4 v[116:119], v41, s[36:37] nt
	global_load_dwordx4 v[120:123], v41, s[36:37] offset:1024 nt
	global_load_dwordx4 v[124:127], v40, s[36:37] nt
	global_load_dwordx4 v[128:131], v40, s[36:37] offset:1024 nt
	global_load_dwordx4 v[132:135], v40, s[36:37] offset:512 nt
	global_load_dwordx4 v[136:139], v40, s[36:37] offset:1536 nt
	v_lshrrev_b32_e32 v38, 5, v2
	v_and_b32_e32 v39, 0x1fff, v38
	v_cmp_gt_u32_e32 vcc, 2, v39
	v_mad_u32_u24 v40, v38, s75, v3
	v_lshl_add_u32 v17, v38, 11, v3
	v_add_u32_e32 v2, s97, v2
	v_cndmask_b32_e64 v41, v205, 0, vcc
	v_cndmask_b32_e64 v18, 1.0, 0, vcc
	v_cmp_eq_u32_e32 vcc, 0, v39
	v_add_u32_e32 v41, v40, v41
	global_load_dwordx4 v[162:165], v41, s[36:37] nt
	global_load_dwordx4 v[166:169], v41, s[36:37] offset:1024 nt
	v_cndmask_b32_e64 v41, v206, 0, vcc
	v_cndmask_b32_e64 v20, 1.0, 0, vcc
	v_add_u32_e32 v41, v40, v41
	global_load_dwordx4 v[170:173], v41, s[36:37] nt
	global_load_dwordx4 v[174:177], v41, s[36:37] offset:1024 nt
	global_load_dwordx4 v[178:181], v40, s[36:37] nt
	global_load_dwordx4 v[182:185], v40, s[36:37] offset:1024 nt
	global_load_dwordx4 v[186:189], v40, s[36:37] offset:512 nt
	global_load_dwordx4 v[190:193], v40, s[36:37] offset:1536 nt
	s_waitcnt vmcnt(0)
	v_lshlrev_b32_e32 v22, 16, v44
	v_and_b32_e32 v23, 0xffff0000, v44
	v_lshlrev_b32_e32 v24, 16, v45
	v_and_b32_e32 v25, 0xffff0000, v45
	v_lshlrev_b32_e32 v26, 16, v46
	v_and_b32_e32 v27, 0xffff0000, v46
	v_lshlrev_b32_e32 v28, 16, v47
	v_and_b32_e32 v29, 0xffff0000, v47
	v_lshlrev_b32_e32 v30, 16, v48
	v_and_b32_e32 v31, 0xffff0000, v48
	v_lshlrev_b32_e32 v32, 16, v49
	v_and_b32_e32 v33, 0xffff0000, v49
	v_lshlrev_b32_e32 v34, 16, v50
	v_and_b32_e32 v35, 0xffff0000, v50
	v_lshlrev_b32_e32 v36, 16, v51
	v_and_b32_e32 v37, 0xffff0000, v51
	v_pk_mul_f32 v[22:23], v[22:23], v[30:31]
	v_pk_mul_f32 v[24:25], v[24:25], v[32:33]
	v_pk_mul_f32 v[26:27], v[26:27], v[34:35]
	v_pk_mul_f32 v[28:29], v[28:29], v[36:37]
	v_pk_mul_f32 v[244:245], v[212:213], v[6:7] op_sel_hi:[1,0]
	v_pk_mul_f32 v[246:247], v[214:215], v[6:7] op_sel_hi:[1,0]
	v_pk_mul_f32 v[248:249], v[216:217], v[6:7] op_sel_hi:[1,0]
	v_pk_mul_f32 v[4:5], v[218:219], v[6:7] op_sel_hi:[1,0]
	v_pk_fma_f32 v[140:141], v[244:245], v[22:23], 0 op_sel_hi:[1,1,0]
	v_pk_fma_f32 v[142:143], v[246:247], v[24:25], 0 op_sel_hi:[1,1,0]
	v_pk_fma_f32 v[144:145], v[248:249], v[26:27], 0 op_sel_hi:[1,1,0]
	v_pk_fma_f32 v[194:195], v[4:5], v[28:29], 0 op_sel_hi:[1,1,0]
	v_lshlrev_b32_e32 v22, 16, v52
	v_and_b32_e32 v23, 0xffff0000, v52
	v_lshlrev_b32_e32 v24, 16, v53
	v_and_b32_e32 v25, 0xffff0000, v53
	v_lshlrev_b32_e32 v26, 16, v54
	v_and_b32_e32 v27, 0xffff0000, v54
	v_lshlrev_b32_e32 v28, 16, v55
	v_and_b32_e32 v29, 0xffff0000, v55
	v_lshlrev_b32_e32 v30, 16, v56
	v_and_b32_e32 v31, 0xffff0000, v56
	v_lshlrev_b32_e32 v32, 16, v57
	v_and_b32_e32 v33, 0xffff0000, v57
	v_lshlrev_b32_e32 v34, 16, v58
	v_and_b32_e32 v35, 0xffff0000, v58
	v_lshlrev_b32_e32 v36, 16, v59
	v_and_b32_e32 v37, 0xffff0000, v59
	v_pk_mul_f32 v[22:23], v[22:23], v[30:31]
	v_pk_mul_f32 v[24:25], v[24:25], v[32:33]
	v_pk_mul_f32 v[26:27], v[26:27], v[34:35]
	v_pk_mul_f32 v[28:29], v[28:29], v[36:37]
	v_pk_mul_f32 v[244:245], v[220:221], v[8:9] op_sel_hi:[1,0]
	v_pk_mul_f32 v[246:247], v[222:223], v[8:9] op_sel_hi:[1,0]
	v_pk_mul_f32 v[248:249], v[224:225], v[8:9] op_sel_hi:[1,0]
	v_pk_mul_f32 v[4:5], v[226:227], v[8:9] op_sel_hi:[1,0]
	v_pk_fma_f32 v[140:141], v[244:245], v[22:23], v[140:141]
	v_pk_fma_f32 v[142:143], v[246:247], v[24:25], v[142:143]
	v_pk_fma_f32 v[144:145], v[248:249], v[26:27], v[144:145]
	v_pk_fma_f32 v[194:195], v[4:5], v[28:29], v[194:195]
	v_lshlrev_b32_e32 v22, 16, v60
	v_and_b32_e32 v23, 0xffff0000, v60
	v_lshlrev_b32_e32 v24, 16, v61
	v_and_b32_e32 v25, 0xffff0000, v61
	v_lshlrev_b32_e32 v26, 16, v62
	v_and_b32_e32 v27, 0xffff0000, v62
	v_lshlrev_b32_e32 v28, 16, v63
	v_and_b32_e32 v29, 0xffff0000, v63
	v_lshlrev_b32_e32 v30, 16, v64
	v_and_b32_e32 v31, 0xffff0000, v64
	v_lshlrev_b32_e32 v32, 16, v65
	v_and_b32_e32 v33, 0xffff0000, v65
	v_lshlrev_b32_e32 v34, 16, v66
	v_and_b32_e32 v35, 0xffff0000, v66
	v_lshlrev_b32_e32 v36, 16, v67
	v_and_b32_e32 v37, 0xffff0000, v67
	v_pk_mul_f32 v[22:23], v[22:23], v[30:31]
	v_pk_mul_f32 v[24:25], v[24:25], v[32:33]
	v_pk_mul_f32 v[26:27], v[26:27], v[34:35]
	v_pk_mul_f32 v[28:29], v[28:29], v[36:37]
	v_pk_fma_f32 v[140:141], v[228:229], v[22:23], v[140:141]
	v_pk_fma_f32 v[142:143], v[230:231], v[24:25], v[142:143]
	v_pk_fma_f32 v[144:145], v[232:233], v[26:27], v[144:145]
	v_pk_fma_f32 v[194:195], v[234:235], v[28:29], v[194:195]
	v_pk_add_f32 v[140:141], v[236:237], v[140:141]
	v_pk_add_f32 v[142:143], v[238:239], v[142:143]
	v_pk_add_f32 v[144:145], v[240:241], v[144:145]
	v_pk_add_f32 v[194:195], v[242:243], v[194:195]
	v_lshlrev_b32_e32 v30, 16, v68
	v_and_b32_e32 v31, 0xffff0000, v68
	v_lshlrev_b32_e32 v32, 16, v69
	v_and_b32_e32 v33, 0xffff0000, v69
	v_lshlrev_b32_e32 v34, 16, v70
	v_and_b32_e32 v35, 0xffff0000, v70
	v_lshlrev_b32_e32 v36, 16, v71
	v_and_b32_e32 v37, 0xffff0000, v71
	v_lshlrev_b32_e32 v22, 16, v72
	v_and_b32_e32 v23, 0xffff0000, v72
	v_lshlrev_b32_e32 v24, 16, v73
	v_and_b32_e32 v25, 0xffff0000, v73
	v_lshlrev_b32_e32 v26, 16, v74
	v_and_b32_e32 v27, 0xffff0000, v74
	v_lshlrev_b32_e32 v28, 16, v75
	v_and_b32_e32 v29, 0xffff0000, v75
	v_pk_mul_f32 v[140:141], v[140:141], v[30:31]
	v_pk_mul_f32 v[142:143], v[142:143], v[32:33]
	v_pk_mul_f32 v[144:145], v[144:145], v[34:35]
	v_pk_mul_f32 v[194:195], v[194:195], v[36:37]
	v_mul_f32_e32 v30, 0xbfb8aa3b, v22
	v_mul_f32_e32 v31, 0xbfb8aa3b, v23
	v_mul_f32_e32 v32, 0xbfb8aa3b, v24
	v_mul_f32_e32 v33, 0xbfb8aa3b, v25
	v_mul_f32_e32 v34, 0xbfb8aa3b, v26
	v_mul_f32_e32 v35, 0xbfb8aa3b, v27
	v_mul_f32_e32 v36, 0xbfb8aa3b, v28
	v_mul_f32_e32 v37, 0xbfb8aa3b, v29
	v_exp_f32_e32 v30, v30
	v_exp_f32_e32 v31, v31
	v_exp_f32_e32 v32, v32
	v_exp_f32_e32 v33, v33
	v_exp_f32_e32 v34, v34
	v_exp_f32_e32 v35, v35
	v_exp_f32_e32 v36, v36
	v_exp_f32_e32 v37, v37
	v_add_f32_e32 v30, 1.0, v30
	v_add_f32_e32 v31, 1.0, v31
	v_add_f32_e32 v32, 1.0, v32
	v_add_f32_e32 v33, 1.0, v33
	v_add_f32_e32 v34, 1.0, v34
	v_add_f32_e32 v35, 1.0, v35
	v_add_f32_e32 v36, 1.0, v36
	v_add_f32_e32 v37, 1.0, v37
	v_rcp_f32_e32 v30, v30
	v_rcp_f32_e32 v31, v31
	v_rcp_f32_e32 v32, v32
	v_rcp_f32_e32 v33, v33
	v_rcp_f32_e32 v34, v34
	v_rcp_f32_e32 v35, v35
	v_rcp_f32_e32 v36, v36
	v_rcp_f32_e32 v37, v37
	v_pk_mul_f32 v[30:31], v[30:31], v[22:23]
	v_pk_mul_f32 v[32:33], v[32:33], v[24:25]
	v_pk_mul_f32 v[34:35], v[34:35], v[26:27]
	v_pk_mul_f32 v[36:37], v[36:37], v[28:29]
	v_pk_mul_f32 v[140:141], v[140:141], v[30:31]
	v_pk_mul_f32 v[142:143], v[142:143], v[32:33]
	v_pk_mul_f32 v[144:145], v[144:145], v[34:35]
	v_pk_mul_f32 v[194:195], v[194:195], v[36:37]
	v_cvt_pk_bf16_f32 v44, v140, v141
	v_cvt_pk_bf16_f32 v45, v142, v143
	v_cvt_pk_bf16_f32 v46, v144, v145
	v_cvt_pk_bf16_f32 v47, v194, v195
	global_store_dwordx4 v42, v[44:47], s[34:35]
	v_lshlrev_b32_e32 v22, 16, v76
	v_and_b32_e32 v23, 0xffff0000, v76
	v_lshlrev_b32_e32 v24, 16, v77
	v_and_b32_e32 v25, 0xffff0000, v77
	v_lshlrev_b32_e32 v26, 16, v78
	v_and_b32_e32 v27, 0xffff0000, v78
	v_lshlrev_b32_e32 v28, 16, v79
	v_and_b32_e32 v29, 0xffff0000, v79
	v_lshlrev_b32_e32 v30, 16, v80
	v_and_b32_e32 v31, 0xffff0000, v80
	v_lshlrev_b32_e32 v32, 16, v81
	v_and_b32_e32 v33, 0xffff0000, v81
	v_lshlrev_b32_e32 v34, 16, v82
	v_and_b32_e32 v35, 0xffff0000, v82
	v_lshlrev_b32_e32 v36, 16, v83
	v_and_b32_e32 v37, 0xffff0000, v83
	v_pk_mul_f32 v[22:23], v[22:23], v[30:31]
	v_pk_mul_f32 v[24:25], v[24:25], v[32:33]
	v_pk_mul_f32 v[26:27], v[26:27], v[34:35]
	v_pk_mul_f32 v[28:29], v[28:29], v[36:37]
	v_pk_mul_f32 v[244:245], v[212:213], v[10:11] op_sel_hi:[1,0]
	v_pk_mul_f32 v[246:247], v[214:215], v[10:11] op_sel_hi:[1,0]
	v_pk_mul_f32 v[248:249], v[216:217], v[10:11] op_sel_hi:[1,0]
	v_pk_mul_f32 v[4:5], v[218:219], v[10:11] op_sel_hi:[1,0]
	v_pk_fma_f32 v[140:141], v[244:245], v[22:23], 0 op_sel_hi:[1,1,0]
	v_pk_fma_f32 v[142:143], v[246:247], v[24:25], 0 op_sel_hi:[1,1,0]
	v_pk_fma_f32 v[144:145], v[248:249], v[26:27], 0 op_sel_hi:[1,1,0]
	v_pk_fma_f32 v[194:195], v[4:5], v[28:29], 0 op_sel_hi:[1,1,0]
	v_lshlrev_b32_e32 v22, 16, v84
	v_and_b32_e32 v23, 0xffff0000, v84
	v_lshlrev_b32_e32 v24, 16, v85
	v_and_b32_e32 v25, 0xffff0000, v85
	v_lshlrev_b32_e32 v26, 16, v86
	v_and_b32_e32 v27, 0xffff0000, v86
	v_lshlrev_b32_e32 v28, 16, v87
	v_and_b32_e32 v29, 0xffff0000, v87
	v_lshlrev_b32_e32 v30, 16, v88
	v_and_b32_e32 v31, 0xffff0000, v88
	v_lshlrev_b32_e32 v32, 16, v89
	v_and_b32_e32 v33, 0xffff0000, v89
	v_lshlrev_b32_e32 v34, 16, v90
	v_and_b32_e32 v35, 0xffff0000, v90
	v_lshlrev_b32_e32 v36, 16, v91
	v_and_b32_e32 v37, 0xffff0000, v91
	v_pk_mul_f32 v[22:23], v[22:23], v[30:31]
	v_pk_mul_f32 v[24:25], v[24:25], v[32:33]
	v_pk_mul_f32 v[26:27], v[26:27], v[34:35]
	v_pk_mul_f32 v[28:29], v[28:29], v[36:37]
	v_pk_mul_f32 v[244:245], v[220:221], v[12:13] op_sel_hi:[1,0]
	v_pk_mul_f32 v[246:247], v[222:223], v[12:13] op_sel_hi:[1,0]
	v_pk_mul_f32 v[248:249], v[224:225], v[12:13] op_sel_hi:[1,0]
	v_pk_mul_f32 v[4:5], v[226:227], v[12:13] op_sel_hi:[1,0]
	v_pk_fma_f32 v[140:141], v[244:245], v[22:23], v[140:141]
	v_pk_fma_f32 v[142:143], v[246:247], v[24:25], v[142:143]
	v_pk_fma_f32 v[144:145], v[248:249], v[26:27], v[144:145]
	v_pk_fma_f32 v[194:195], v[4:5], v[28:29], v[194:195]
	v_lshlrev_b32_e32 v22, 16, v92
	v_and_b32_e32 v23, 0xffff0000, v92
	v_lshlrev_b32_e32 v24, 16, v93
	v_and_b32_e32 v25, 0xffff0000, v93
	v_lshlrev_b32_e32 v26, 16, v94
	v_and_b32_e32 v27, 0xffff0000, v94
	v_lshlrev_b32_e32 v28, 16, v95
	v_and_b32_e32 v29, 0xffff0000, v95
	v_lshlrev_b32_e32 v30, 16, v96
	v_and_b32_e32 v31, 0xffff0000, v96
	v_lshlrev_b32_e32 v32, 16, v97
	v_and_b32_e32 v33, 0xffff0000, v97
	v_lshlrev_b32_e32 v34, 16, v98
	v_and_b32_e32 v35, 0xffff0000, v98
	v_lshlrev_b32_e32 v36, 16, v99
	v_and_b32_e32 v37, 0xffff0000, v99
	v_pk_mul_f32 v[22:23], v[22:23], v[30:31]
	v_pk_mul_f32 v[24:25], v[24:25], v[32:33]
	v_pk_mul_f32 v[26:27], v[26:27], v[34:35]
	v_pk_mul_f32 v[28:29], v[28:29], v[36:37]
	v_pk_fma_f32 v[140:141], v[228:229], v[22:23], v[140:141]
	v_pk_fma_f32 v[142:143], v[230:231], v[24:25], v[142:143]
	v_pk_fma_f32 v[144:145], v[232:233], v[26:27], v[144:145]
	v_pk_fma_f32 v[194:195], v[234:235], v[28:29], v[194:195]
	v_pk_add_f32 v[140:141], v[236:237], v[140:141]
	v_pk_add_f32 v[142:143], v[238:239], v[142:143]
	v_pk_add_f32 v[144:145], v[240:241], v[144:145]
	v_pk_add_f32 v[194:195], v[242:243], v[194:195]
	v_lshlrev_b32_e32 v30, 16, v100
	v_and_b32_e32 v31, 0xffff0000, v100
	v_lshlrev_b32_e32 v32, 16, v101
	v_and_b32_e32 v33, 0xffff0000, v101
	v_lshlrev_b32_e32 v34, 16, v102
	v_and_b32_e32 v35, 0xffff0000, v102
	v_lshlrev_b32_e32 v36, 16, v103
	v_and_b32_e32 v37, 0xffff0000, v103
	v_lshlrev_b32_e32 v22, 16, v104
	v_and_b32_e32 v23, 0xffff0000, v104
	v_lshlrev_b32_e32 v24, 16, v105
	v_and_b32_e32 v25, 0xffff0000, v105
	v_lshlrev_b32_e32 v26, 16, v106
	v_and_b32_e32 v27, 0xffff0000, v106
	v_lshlrev_b32_e32 v28, 16, v107
	v_and_b32_e32 v29, 0xffff0000, v107
	v_pk_mul_f32 v[140:141], v[140:141], v[30:31]
	v_pk_mul_f32 v[142:143], v[142:143], v[32:33]
	v_pk_mul_f32 v[144:145], v[144:145], v[34:35]
	v_pk_mul_f32 v[194:195], v[194:195], v[36:37]
	v_mul_f32_e32 v30, 0xbfb8aa3b, v22
	v_mul_f32_e32 v31, 0xbfb8aa3b, v23
	v_mul_f32_e32 v32, 0xbfb8aa3b, v24
	v_mul_f32_e32 v33, 0xbfb8aa3b, v25
	v_mul_f32_e32 v34, 0xbfb8aa3b, v26
	v_mul_f32_e32 v35, 0xbfb8aa3b, v27
	v_mul_f32_e32 v36, 0xbfb8aa3b, v28
	v_mul_f32_e32 v37, 0xbfb8aa3b, v29
	v_exp_f32_e32 v30, v30
	v_exp_f32_e32 v31, v31
	v_exp_f32_e32 v32, v32
	v_exp_f32_e32 v33, v33
	v_exp_f32_e32 v34, v34
	v_exp_f32_e32 v35, v35
	v_exp_f32_e32 v36, v36
	v_exp_f32_e32 v37, v37
	v_add_f32_e32 v30, 1.0, v30
	v_add_f32_e32 v31, 1.0, v31
	v_add_f32_e32 v32, 1.0, v32
	v_add_f32_e32 v33, 1.0, v33
	v_add_f32_e32 v34, 1.0, v34
	v_add_f32_e32 v35, 1.0, v35
	v_add_f32_e32 v36, 1.0, v36
	v_add_f32_e32 v37, 1.0, v37
	v_rcp_f32_e32 v30, v30
	v_rcp_f32_e32 v31, v31
	v_rcp_f32_e32 v32, v32
	v_rcp_f32_e32 v33, v33
	v_rcp_f32_e32 v34, v34
	v_rcp_f32_e32 v35, v35
	v_rcp_f32_e32 v36, v36
	v_rcp_f32_e32 v37, v37
	v_pk_mul_f32 v[30:31], v[30:31], v[22:23]
	v_pk_mul_f32 v[32:33], v[32:33], v[24:25]
	v_pk_mul_f32 v[34:35], v[34:35], v[26:27]
	v_pk_mul_f32 v[36:37], v[36:37], v[28:29]
	v_pk_mul_f32 v[140:141], v[140:141], v[30:31]
	v_pk_mul_f32 v[142:143], v[142:143], v[32:33]
	v_pk_mul_f32 v[144:145], v[144:145], v[34:35]
	v_pk_mul_f32 v[194:195], v[194:195], v[36:37]
	v_cvt_pk_bf16_f32 v76, v140, v141
	v_cvt_pk_bf16_f32 v77, v142, v143
	v_cvt_pk_bf16_f32 v78, v144, v145
	v_cvt_pk_bf16_f32 v79, v194, v195
	global_store_dwordx4 v9, v[76:79], s[34:35]
	v_lshlrev_b32_e32 v22, 16, v108
	v_and_b32_e32 v23, 0xffff0000, v108
	v_lshlrev_b32_e32 v24, 16, v109
	v_and_b32_e32 v25, 0xffff0000, v109
	v_lshlrev_b32_e32 v26, 16, v110
	v_and_b32_e32 v27, 0xffff0000, v110
	v_lshlrev_b32_e32 v28, 16, v111
	v_and_b32_e32 v29, 0xffff0000, v111
	v_lshlrev_b32_e32 v30, 16, v112
	v_and_b32_e32 v31, 0xffff0000, v112
	v_lshlrev_b32_e32 v32, 16, v113
	v_and_b32_e32 v33, 0xffff0000, v113
	v_lshlrev_b32_e32 v34, 16, v114
	v_and_b32_e32 v35, 0xffff0000, v114
	v_lshlrev_b32_e32 v36, 16, v115
	v_and_b32_e32 v37, 0xffff0000, v115
	v_pk_mul_f32 v[22:23], v[22:23], v[30:31]
	v_pk_mul_f32 v[24:25], v[24:25], v[32:33]
	v_pk_mul_f32 v[26:27], v[26:27], v[34:35]
	v_pk_mul_f32 v[28:29], v[28:29], v[36:37]
	v_pk_mul_f32 v[244:245], v[212:213], v[14:15] op_sel_hi:[1,0]
	v_pk_mul_f32 v[246:247], v[214:215], v[14:15] op_sel_hi:[1,0]
	v_pk_mul_f32 v[248:249], v[216:217], v[14:15] op_sel_hi:[1,0]
	v_pk_mul_f32 v[4:5], v[218:219], v[14:15] op_sel_hi:[1,0]
	v_pk_fma_f32 v[140:141], v[244:245], v[22:23], 0 op_sel_hi:[1,1,0]
	v_pk_fma_f32 v[142:143], v[246:247], v[24:25], 0 op_sel_hi:[1,1,0]
	v_pk_fma_f32 v[144:145], v[248:249], v[26:27], 0 op_sel_hi:[1,1,0]
	v_pk_fma_f32 v[194:195], v[4:5], v[28:29], 0 op_sel_hi:[1,1,0]
	v_lshlrev_b32_e32 v22, 16, v116
	v_and_b32_e32 v23, 0xffff0000, v116
	v_lshlrev_b32_e32 v24, 16, v117
	v_and_b32_e32 v25, 0xffff0000, v117
	v_lshlrev_b32_e32 v26, 16, v118
	v_and_b32_e32 v27, 0xffff0000, v118
	v_lshlrev_b32_e32 v28, 16, v119
	v_and_b32_e32 v29, 0xffff0000, v119
	v_lshlrev_b32_e32 v30, 16, v120
	v_and_b32_e32 v31, 0xffff0000, v120
	v_lshlrev_b32_e32 v32, 16, v121
	v_and_b32_e32 v33, 0xffff0000, v121
	v_lshlrev_b32_e32 v34, 16, v122
	v_and_b32_e32 v35, 0xffff0000, v122
	v_lshlrev_b32_e32 v36, 16, v123
	v_and_b32_e32 v37, 0xffff0000, v123
	v_pk_mul_f32 v[22:23], v[22:23], v[30:31]
	v_pk_mul_f32 v[24:25], v[24:25], v[32:33]
	v_pk_mul_f32 v[26:27], v[26:27], v[34:35]
	v_pk_mul_f32 v[28:29], v[28:29], v[36:37]
	v_pk_mul_f32 v[244:245], v[220:221], v[16:17] op_sel_hi:[1,0]
	v_pk_mul_f32 v[246:247], v[222:223], v[16:17] op_sel_hi:[1,0]
	v_pk_mul_f32 v[248:249], v[224:225], v[16:17] op_sel_hi:[1,0]
	v_pk_mul_f32 v[4:5], v[226:227], v[16:17] op_sel_hi:[1,0]
	v_pk_fma_f32 v[140:141], v[244:245], v[22:23], v[140:141]
	v_pk_fma_f32 v[142:143], v[246:247], v[24:25], v[142:143]
	v_pk_fma_f32 v[144:145], v[248:249], v[26:27], v[144:145]
	v_pk_fma_f32 v[194:195], v[4:5], v[28:29], v[194:195]
	v_lshlrev_b32_e32 v22, 16, v124
	v_and_b32_e32 v23, 0xffff0000, v124
	v_lshlrev_b32_e32 v24, 16, v125
	v_and_b32_e32 v25, 0xffff0000, v125
	v_lshlrev_b32_e32 v26, 16, v126
	v_and_b32_e32 v27, 0xffff0000, v126
	v_lshlrev_b32_e32 v28, 16, v127
	v_and_b32_e32 v29, 0xffff0000, v127
	v_lshlrev_b32_e32 v30, 16, v128
	v_and_b32_e32 v31, 0xffff0000, v128
	v_lshlrev_b32_e32 v32, 16, v129
	v_and_b32_e32 v33, 0xffff0000, v129
	v_lshlrev_b32_e32 v34, 16, v130
	v_and_b32_e32 v35, 0xffff0000, v130
	v_lshlrev_b32_e32 v36, 16, v131
	v_and_b32_e32 v37, 0xffff0000, v131
	v_pk_mul_f32 v[22:23], v[22:23], v[30:31]
	v_pk_mul_f32 v[24:25], v[24:25], v[32:33]
	v_pk_mul_f32 v[26:27], v[26:27], v[34:35]
	v_pk_mul_f32 v[28:29], v[28:29], v[36:37]
	v_pk_fma_f32 v[140:141], v[228:229], v[22:23], v[140:141]
	v_pk_fma_f32 v[142:143], v[230:231], v[24:25], v[142:143]
	v_pk_fma_f32 v[144:145], v[232:233], v[26:27], v[144:145]
	v_pk_fma_f32 v[194:195], v[234:235], v[28:29], v[194:195]
	v_pk_add_f32 v[140:141], v[236:237], v[140:141]
	v_pk_add_f32 v[142:143], v[238:239], v[142:143]
	v_pk_add_f32 v[144:145], v[240:241], v[144:145]
	v_pk_add_f32 v[194:195], v[242:243], v[194:195]
	v_lshlrev_b32_e32 v30, 16, v132
	v_and_b32_e32 v31, 0xffff0000, v132
	v_lshlrev_b32_e32 v32, 16, v133
	v_and_b32_e32 v33, 0xffff0000, v133
	v_lshlrev_b32_e32 v34, 16, v134
	v_and_b32_e32 v35, 0xffff0000, v134
	v_lshlrev_b32_e32 v36, 16, v135
	v_and_b32_e32 v37, 0xffff0000, v135
	v_lshlrev_b32_e32 v22, 16, v136
	v_and_b32_e32 v23, 0xffff0000, v136
	v_lshlrev_b32_e32 v24, 16, v137
	v_and_b32_e32 v25, 0xffff0000, v137
	v_lshlrev_b32_e32 v26, 16, v138
	v_and_b32_e32 v27, 0xffff0000, v138
	v_lshlrev_b32_e32 v28, 16, v139
	v_and_b32_e32 v29, 0xffff0000, v139
	v_pk_mul_f32 v[140:141], v[140:141], v[30:31]
	v_pk_mul_f32 v[142:143], v[142:143], v[32:33]
	v_pk_mul_f32 v[144:145], v[144:145], v[34:35]
	v_pk_mul_f32 v[194:195], v[194:195], v[36:37]
	v_mul_f32_e32 v30, 0xbfb8aa3b, v22
	v_mul_f32_e32 v31, 0xbfb8aa3b, v23
	v_mul_f32_e32 v32, 0xbfb8aa3b, v24
	v_mul_f32_e32 v33, 0xbfb8aa3b, v25
	v_mul_f32_e32 v34, 0xbfb8aa3b, v26
	v_mul_f32_e32 v35, 0xbfb8aa3b, v27
	v_mul_f32_e32 v36, 0xbfb8aa3b, v28
	v_mul_f32_e32 v37, 0xbfb8aa3b, v29
	v_exp_f32_e32 v30, v30
	v_exp_f32_e32 v31, v31
	v_exp_f32_e32 v32, v32
	v_exp_f32_e32 v33, v33
	v_exp_f32_e32 v34, v34
	v_exp_f32_e32 v35, v35
	v_exp_f32_e32 v36, v36
	v_exp_f32_e32 v37, v37
	v_add_f32_e32 v30, 1.0, v30
	v_add_f32_e32 v31, 1.0, v31
	v_add_f32_e32 v32, 1.0, v32
	v_add_f32_e32 v33, 1.0, v33
	v_add_f32_e32 v34, 1.0, v34
	v_add_f32_e32 v35, 1.0, v35
	v_add_f32_e32 v36, 1.0, v36
	v_add_f32_e32 v37, 1.0, v37
	v_rcp_f32_e32 v30, v30
	v_rcp_f32_e32 v31, v31
	v_rcp_f32_e32 v32, v32
	v_rcp_f32_e32 v33, v33
	v_rcp_f32_e32 v34, v34
	v_rcp_f32_e32 v35, v35
	v_rcp_f32_e32 v36, v36
	v_rcp_f32_e32 v37, v37
	v_pk_mul_f32 v[30:31], v[30:31], v[22:23]
	v_pk_mul_f32 v[32:33], v[32:33], v[24:25]
	v_pk_mul_f32 v[34:35], v[34:35], v[26:27]
	v_pk_mul_f32 v[36:37], v[36:37], v[28:29]
	v_pk_mul_f32 v[140:141], v[140:141], v[30:31]
	v_pk_mul_f32 v[142:143], v[142:143], v[32:33]
	v_pk_mul_f32 v[144:145], v[144:145], v[34:35]
	v_pk_mul_f32 v[194:195], v[194:195], v[36:37]
	v_cvt_pk_bf16_f32 v108, v140, v141
	v_cvt_pk_bf16_f32 v109, v142, v143
	v_cvt_pk_bf16_f32 v110, v144, v145
	v_cvt_pk_bf16_f32 v111, v194, v195
	global_store_dwordx4 v13, v[108:111], s[34:35]
	v_lshlrev_b32_e32 v22, 16, v162
	v_and_b32_e32 v23, 0xffff0000, v162
	v_lshlrev_b32_e32 v24, 16, v163
	v_and_b32_e32 v25, 0xffff0000, v163
	v_lshlrev_b32_e32 v26, 16, v164
	v_and_b32_e32 v27, 0xffff0000, v164
	v_lshlrev_b32_e32 v28, 16, v165
	v_and_b32_e32 v29, 0xffff0000, v165
	v_lshlrev_b32_e32 v30, 16, v166
	v_and_b32_e32 v31, 0xffff0000, v166
	v_lshlrev_b32_e32 v32, 16, v167
	v_and_b32_e32 v33, 0xffff0000, v167
	v_lshlrev_b32_e32 v34, 16, v168
	v_and_b32_e32 v35, 0xffff0000, v168
	v_lshlrev_b32_e32 v36, 16, v169
	v_and_b32_e32 v37, 0xffff0000, v169
	v_pk_mul_f32 v[22:23], v[22:23], v[30:31]
	v_pk_mul_f32 v[24:25], v[24:25], v[32:33]
	v_pk_mul_f32 v[26:27], v[26:27], v[34:35]
	v_pk_mul_f32 v[28:29], v[28:29], v[36:37]
	v_pk_mul_f32 v[244:245], v[212:213], v[18:19] op_sel_hi:[1,0]
	v_pk_mul_f32 v[246:247], v[214:215], v[18:19] op_sel_hi:[1,0]
	v_pk_mul_f32 v[248:249], v[216:217], v[18:19] op_sel_hi:[1,0]
	v_pk_mul_f32 v[4:5], v[218:219], v[18:19] op_sel_hi:[1,0]
	v_pk_fma_f32 v[140:141], v[244:245], v[22:23], 0 op_sel_hi:[1,1,0]
	v_pk_fma_f32 v[142:143], v[246:247], v[24:25], 0 op_sel_hi:[1,1,0]
	v_pk_fma_f32 v[144:145], v[248:249], v[26:27], 0 op_sel_hi:[1,1,0]
	v_pk_fma_f32 v[194:195], v[4:5], v[28:29], 0 op_sel_hi:[1,1,0]
	v_lshlrev_b32_e32 v22, 16, v170
	v_and_b32_e32 v23, 0xffff0000, v170
	v_lshlrev_b32_e32 v24, 16, v171
	v_and_b32_e32 v25, 0xffff0000, v171
	v_lshlrev_b32_e32 v26, 16, v172
	v_and_b32_e32 v27, 0xffff0000, v172
	v_lshlrev_b32_e32 v28, 16, v173
	v_and_b32_e32 v29, 0xffff0000, v173
	v_lshlrev_b32_e32 v30, 16, v174
	v_and_b32_e32 v31, 0xffff0000, v174
	v_lshlrev_b32_e32 v32, 16, v175
	v_and_b32_e32 v33, 0xffff0000, v175
	v_lshlrev_b32_e32 v34, 16, v176
	v_and_b32_e32 v35, 0xffff0000, v176
	v_lshlrev_b32_e32 v36, 16, v177
	v_and_b32_e32 v37, 0xffff0000, v177
	v_pk_mul_f32 v[22:23], v[22:23], v[30:31]
	v_pk_mul_f32 v[24:25], v[24:25], v[32:33]
	v_pk_mul_f32 v[26:27], v[26:27], v[34:35]
	v_pk_mul_f32 v[28:29], v[28:29], v[36:37]
	v_pk_mul_f32 v[244:245], v[220:221], v[20:21] op_sel_hi:[1,0]
	v_pk_mul_f32 v[246:247], v[222:223], v[20:21] op_sel_hi:[1,0]
	v_pk_mul_f32 v[248:249], v[224:225], v[20:21] op_sel_hi:[1,0]
	v_pk_mul_f32 v[4:5], v[226:227], v[20:21] op_sel_hi:[1,0]
	v_pk_fma_f32 v[140:141], v[244:245], v[22:23], v[140:141]
	v_pk_fma_f32 v[142:143], v[246:247], v[24:25], v[142:143]
	v_pk_fma_f32 v[144:145], v[248:249], v[26:27], v[144:145]
	v_pk_fma_f32 v[194:195], v[4:5], v[28:29], v[194:195]
	v_lshlrev_b32_e32 v22, 16, v178
	v_and_b32_e32 v23, 0xffff0000, v178
	v_lshlrev_b32_e32 v24, 16, v179
	v_and_b32_e32 v25, 0xffff0000, v179
	v_lshlrev_b32_e32 v26, 16, v180
	v_and_b32_e32 v27, 0xffff0000, v180
	v_lshlrev_b32_e32 v28, 16, v181
	v_and_b32_e32 v29, 0xffff0000, v181
	v_lshlrev_b32_e32 v30, 16, v182
	v_and_b32_e32 v31, 0xffff0000, v182
	v_lshlrev_b32_e32 v32, 16, v183
	v_and_b32_e32 v33, 0xffff0000, v183
	v_lshlrev_b32_e32 v34, 16, v184
	v_and_b32_e32 v35, 0xffff0000, v184
	v_lshlrev_b32_e32 v36, 16, v185
	v_and_b32_e32 v37, 0xffff0000, v185
	v_pk_mul_f32 v[22:23], v[22:23], v[30:31]
	v_pk_mul_f32 v[24:25], v[24:25], v[32:33]
	v_pk_mul_f32 v[26:27], v[26:27], v[34:35]
	v_pk_mul_f32 v[28:29], v[28:29], v[36:37]
	v_pk_fma_f32 v[140:141], v[228:229], v[22:23], v[140:141]
	v_pk_fma_f32 v[142:143], v[230:231], v[24:25], v[142:143]
	v_pk_fma_f32 v[144:145], v[232:233], v[26:27], v[144:145]
	v_pk_fma_f32 v[194:195], v[234:235], v[28:29], v[194:195]
	v_pk_add_f32 v[140:141], v[236:237], v[140:141]
	v_pk_add_f32 v[142:143], v[238:239], v[142:143]
	v_pk_add_f32 v[144:145], v[240:241], v[144:145]
	v_pk_add_f32 v[194:195], v[242:243], v[194:195]
	v_lshlrev_b32_e32 v30, 16, v186
	v_and_b32_e32 v31, 0xffff0000, v186
	v_lshlrev_b32_e32 v32, 16, v187
	v_and_b32_e32 v33, 0xffff0000, v187
	v_lshlrev_b32_e32 v34, 16, v188
	v_and_b32_e32 v35, 0xffff0000, v188
	v_lshlrev_b32_e32 v36, 16, v189
	v_and_b32_e32 v37, 0xffff0000, v189
	v_lshlrev_b32_e32 v22, 16, v190
	v_and_b32_e32 v23, 0xffff0000, v190
	v_lshlrev_b32_e32 v24, 16, v191
	v_and_b32_e32 v25, 0xffff0000, v191
	v_lshlrev_b32_e32 v26, 16, v192
	v_and_b32_e32 v27, 0xffff0000, v192
	v_lshlrev_b32_e32 v28, 16, v193
	v_and_b32_e32 v29, 0xffff0000, v193
	v_pk_mul_f32 v[140:141], v[140:141], v[30:31]
	v_pk_mul_f32 v[142:143], v[142:143], v[32:33]
	v_pk_mul_f32 v[144:145], v[144:145], v[34:35]
	v_pk_mul_f32 v[194:195], v[194:195], v[36:37]
	v_mul_f32_e32 v30, 0xbfb8aa3b, v22
	v_mul_f32_e32 v31, 0xbfb8aa3b, v23
	v_mul_f32_e32 v32, 0xbfb8aa3b, v24
	v_mul_f32_e32 v33, 0xbfb8aa3b, v25
	v_mul_f32_e32 v34, 0xbfb8aa3b, v26
	v_mul_f32_e32 v35, 0xbfb8aa3b, v27
	v_mul_f32_e32 v36, 0xbfb8aa3b, v28
	v_mul_f32_e32 v37, 0xbfb8aa3b, v29
	v_exp_f32_e32 v30, v30
	v_exp_f32_e32 v31, v31
	v_exp_f32_e32 v32, v32
	v_exp_f32_e32 v33, v33
	v_exp_f32_e32 v34, v34
	v_exp_f32_e32 v35, v35
	v_exp_f32_e32 v36, v36
	v_exp_f32_e32 v37, v37
	v_add_f32_e32 v30, 1.0, v30
	v_add_f32_e32 v31, 1.0, v31
	v_add_f32_e32 v32, 1.0, v32
	v_add_f32_e32 v33, 1.0, v33
	v_add_f32_e32 v34, 1.0, v34
	v_add_f32_e32 v35, 1.0, v35
	v_add_f32_e32 v36, 1.0, v36
	v_add_f32_e32 v37, 1.0, v37
	v_rcp_f32_e32 v30, v30
	v_rcp_f32_e32 v31, v31
	v_rcp_f32_e32 v32, v32
	v_rcp_f32_e32 v33, v33
	v_rcp_f32_e32 v34, v34
	v_rcp_f32_e32 v35, v35
	v_rcp_f32_e32 v36, v36
	v_rcp_f32_e32 v37, v37
	v_pk_mul_f32 v[30:31], v[30:31], v[22:23]
	v_pk_mul_f32 v[32:33], v[32:33], v[24:25]
	v_pk_mul_f32 v[34:35], v[34:35], v[26:27]
	v_pk_mul_f32 v[36:37], v[36:37], v[28:29]
	v_pk_mul_f32 v[140:141], v[140:141], v[30:31]
	v_pk_mul_f32 v[142:143], v[142:143], v[32:33]
	v_pk_mul_f32 v[144:145], v[144:145], v[34:35]
	v_pk_mul_f32 v[194:195], v[194:195], v[36:37]
	v_cvt_pk_bf16_f32 v162, v140, v141
	v_cvt_pk_bf16_f32 v163, v142, v143
	v_cvt_pk_bf16_f32 v164, v144, v145
	v_cvt_pk_bf16_f32 v165, v194, v195
	global_store_dwordx4 v17, v[162:165], s[34:35]
	s_mov_b64 s[2:3], exec

.LBB0_261:
	v_and_b32_e32 v41, 31, v4
	v_and_b32_e32 v42, 7, v4
	v_lshrrev_b32_e32 v40, 5, v4
	v_lshlrev_b32_e32 v41, 4, v41
	v_lshlrev_b32_e32 v42, 5, v42
	global_load_dwordx4 v[212:215], v42, s[0:1]
	global_load_dwordx4 v[216:219], v42, s[0:1] offset:16
	global_load_dwordx4 v[220:223], v42, s[4:5]
	global_load_dwordx4 v[224:227], v42, s[4:5] offset:16
	s_lshr_b32 s12, s97, 5
	v_mad_u32_u24 v108, v40, s75, v41
	v_add_u32_e32 v40, s12, v40
	global_load_dwordx4 v[44:47], v108, s[36:37] offset:2048 nt
	global_load_dwordx4 v[48:51], v108, s[36:37] offset:2560 nt
	v_mad_u32_u24 v109, v40, s75, v41
	v_add_u32_e32 v40, s12, v40
	global_load_dwordx4 v[52:55], v109, s[36:37] offset:2048 nt
	global_load_dwordx4 v[56:59], v109, s[36:37] offset:2560 nt
	v_mad_u32_u24 v110, v40, s75, v41
	v_add_u32_e32 v40, s12, v40
	global_load_dwordx4 v[60:63], v110, s[36:37] offset:2048 nt
	global_load_dwordx4 v[64:67], v110, s[36:37] offset:2560 nt
	v_mad_u32_u24 v111, v40, s75, v41
	v_add_u32_e32 v40, s12, v40
	global_load_dwordx4 v[68:71], v111, s[36:37] offset:2048 nt
	global_load_dwordx4 v[72:75], v111, s[36:37] offset:2560 nt
	v_mad_u32_u24 v112, v40, s75, v41
	v_add_u32_e32 v40, s12, v40
	global_load_dwordx4 v[76:79], v112, s[36:37] offset:2048 nt
	global_load_dwordx4 v[80:83], v112, s[36:37] offset:2560 nt
	v_mad_u32_u24 v113, v40, s75, v41
	v_add_u32_e32 v40, s12, v40
	global_load_dwordx4 v[84:87], v113, s[36:37] offset:2048 nt
	global_load_dwordx4 v[88:91], v113, s[36:37] offset:2560 nt
	v_mad_u32_u24 v114, v40, s75, v41
	v_add_u32_e32 v40, s12, v40
	global_load_dwordx4 v[92:95], v114, s[36:37] offset:2048 nt
	global_load_dwordx4 v[96:99], v114, s[36:37] offset:2560 nt
	v_mad_u32_u24 v115, v40, s75, v41
	global_load_dwordx4 v[100:103], v115, s[36:37] offset:2048 nt
	global_load_dwordx4 v[104:107], v115, s[36:37] offset:2560 nt
	s_waitcnt vmcnt(0)
	v_lshlrev_b32_e32 v22, 16, v44
	v_and_b32_e32 v23, 0xffff0000, v44
	v_lshlrev_b32_e32 v24, 16, v45
	v_and_b32_e32 v25, 0xffff0000, v45
	v_lshlrev_b32_e32 v26, 16, v46
	v_and_b32_e32 v27, 0xffff0000, v46
	v_lshlrev_b32_e32 v28, 16, v47
	v_and_b32_e32 v29, 0xffff0000, v47
	v_mul_f32_e32 v30, v23, v23
	v_mul_f32_e32 v31, v25, v25
	v_mul_f32_e32 v32, v27, v27
	v_mul_f32_e32 v33, v29, v29
	v_fmac_f32_e32 v30, v22, v22
	v_fmac_f32_e32 v31, v24, v24
	v_fmac_f32_e32 v32, v26, v26
	v_fmac_f32_e32 v33, v28, v28
	v_add_f32_e32 v116, v30, v31
	v_add_f32_e32 v116, v32, v116
	v_add_f32_e32 v116, v33, v116
	v_lshlrev_b32_e32 v22, 16, v48
	v_and_b32_e32 v23, 0xffff0000, v48
	v_lshlrev_b32_e32 v24, 16, v49
	v_and_b32_e32 v25, 0xffff0000, v49
	v_lshlrev_b32_e32 v26, 16, v50
	v_and_b32_e32 v27, 0xffff0000, v50
	v_lshlrev_b32_e32 v28, 16, v51
	v_and_b32_e32 v29, 0xffff0000, v51
	v_mul_f32_e32 v30, v23, v23
	v_mul_f32_e32 v31, v25, v25
	v_mul_f32_e32 v32, v27, v27
	v_mul_f32_e32 v33, v29, v29
	v_fmac_f32_e32 v30, v22, v22
	v_fmac_f32_e32 v31, v24, v24
	v_fmac_f32_e32 v32, v26, v26
	v_fmac_f32_e32 v33, v28, v28
	v_add_f32_e32 v124, v30, v31
	v_add_f32_e32 v124, v32, v124
	v_add_f32_e32 v124, v33, v124
	v_lshlrev_b32_e32 v22, 16, v52
	v_and_b32_e32 v23, 0xffff0000, v52
	v_lshlrev_b32_e32 v24, 16, v53
	v_and_b32_e32 v25, 0xffff0000, v53
	v_lshlrev_b32_e32 v26, 16, v54
	v_and_b32_e32 v27, 0xffff0000, v54
	v_lshlrev_b32_e32 v28, 16, v55
	v_and_b32_e32 v29, 0xffff0000, v55
	v_mul_f32_e32 v30, v23, v23
	v_mul_f32_e32 v31, v25, v25
	v_mul_f32_e32 v32, v27, v27
	v_mul_f32_e32 v33, v29, v29
	v_fmac_f32_e32 v30, v22, v22
	v_fmac_f32_e32 v31, v24, v24
	v_fmac_f32_e32 v32, v26, v26
	v_fmac_f32_e32 v33, v28, v28
	v_add_f32_e32 v117, v30, v31
	v_add_f32_e32 v117, v32, v117
	v_add_f32_e32 v117, v33, v117
	v_lshlrev_b32_e32 v22, 16, v56
	v_and_b32_e32 v23, 0xffff0000, v56
	v_lshlrev_b32_e32 v24, 16, v57
	v_and_b32_e32 v25, 0xffff0000, v57
	v_lshlrev_b32_e32 v26, 16, v58
	v_and_b32_e32 v27, 0xffff0000, v58
	v_lshlrev_b32_e32 v28, 16, v59
	v_and_b32_e32 v29, 0xffff0000, v59
	v_mul_f32_e32 v30, v23, v23
	v_mul_f32_e32 v31, v25, v25
	v_mul_f32_e32 v32, v27, v27
	v_mul_f32_e32 v33, v29, v29
	v_fmac_f32_e32 v30, v22, v22
	v_fmac_f32_e32 v31, v24, v24
	v_fmac_f32_e32 v32, v26, v26
	v_fmac_f32_e32 v33, v28, v28
	v_add_f32_e32 v125, v30, v31
	v_add_f32_e32 v125, v32, v125
	v_add_f32_e32 v125, v33, v125
	v_lshlrev_b32_e32 v22, 16, v60
	v_and_b32_e32 v23, 0xffff0000, v60
	v_lshlrev_b32_e32 v24, 16, v61
	v_and_b32_e32 v25, 0xffff0000, v61
	v_lshlrev_b32_e32 v26, 16, v62
	v_and_b32_e32 v27, 0xffff0000, v62
	v_lshlrev_b32_e32 v28, 16, v63
	v_and_b32_e32 v29, 0xffff0000, v63
	v_mul_f32_e32 v30, v23, v23
	v_mul_f32_e32 v31, v25, v25
	v_mul_f32_e32 v32, v27, v27
	v_mul_f32_e32 v33, v29, v29
	v_fmac_f32_e32 v30, v22, v22
	v_fmac_f32_e32 v31, v24, v24
	v_fmac_f32_e32 v32, v26, v26
	v_fmac_f32_e32 v33, v28, v28
	v_add_f32_e32 v118, v30, v31
	v_add_f32_e32 v118, v32, v118
	v_add_f32_e32 v118, v33, v118
	v_lshlrev_b32_e32 v22, 16, v64
	v_and_b32_e32 v23, 0xffff0000, v64
	v_lshlrev_b32_e32 v24, 16, v65
	v_and_b32_e32 v25, 0xffff0000, v65
	v_lshlrev_b32_e32 v26, 16, v66
	v_and_b32_e32 v27, 0xffff0000, v66
	v_lshlrev_b32_e32 v28, 16, v67
	v_and_b32_e32 v29, 0xffff0000, v67
	v_mul_f32_e32 v30, v23, v23
	v_mul_f32_e32 v31, v25, v25
	v_mul_f32_e32 v32, v27, v27
	v_mul_f32_e32 v33, v29, v29
	v_fmac_f32_e32 v30, v22, v22
	v_fmac_f32_e32 v31, v24, v24
	v_fmac_f32_e32 v32, v26, v26
	v_fmac_f32_e32 v33, v28, v28
	v_add_f32_e32 v126, v30, v31
	v_add_f32_e32 v126, v32, v126
	v_add_f32_e32 v126, v33, v126
	v_lshlrev_b32_e32 v22, 16, v68
	v_and_b32_e32 v23, 0xffff0000, v68
	v_lshlrev_b32_e32 v24, 16, v69
	v_and_b32_e32 v25, 0xffff0000, v69
	v_lshlrev_b32_e32 v26, 16, v70
	v_and_b32_e32 v27, 0xffff0000, v70
	v_lshlrev_b32_e32 v28, 16, v71
	v_and_b32_e32 v29, 0xffff0000, v71
	v_mul_f32_e32 v30, v23, v23
	v_mul_f32_e32 v31, v25, v25
	v_mul_f32_e32 v32, v27, v27
	v_mul_f32_e32 v33, v29, v29
	v_fmac_f32_e32 v30, v22, v22
	v_fmac_f32_e32 v31, v24, v24
	v_fmac_f32_e32 v32, v26, v26
	v_fmac_f32_e32 v33, v28, v28
	v_add_f32_e32 v119, v30, v31
	v_add_f32_e32 v119, v32, v119
	v_add_f32_e32 v119, v33, v119
	v_lshlrev_b32_e32 v22, 16, v72
	v_and_b32_e32 v23, 0xffff0000, v72
	v_lshlrev_b32_e32 v24, 16, v73
	v_and_b32_e32 v25, 0xffff0000, v73
	v_lshlrev_b32_e32 v26, 16, v74
	v_and_b32_e32 v27, 0xffff0000, v74
	v_lshlrev_b32_e32 v28, 16, v75
	v_and_b32_e32 v29, 0xffff0000, v75
	v_mul_f32_e32 v30, v23, v23
	v_mul_f32_e32 v31, v25, v25
	v_mul_f32_e32 v32, v27, v27
	v_mul_f32_e32 v33, v29, v29
	v_fmac_f32_e32 v30, v22, v22
	v_fmac_f32_e32 v31, v24, v24
	v_fmac_f32_e32 v32, v26, v26
	v_fmac_f32_e32 v33, v28, v28
	v_add_f32_e32 v127, v30, v31
	v_add_f32_e32 v127, v32, v127
	v_add_f32_e32 v127, v33, v127
	v_lshlrev_b32_e32 v22, 16, v76
	v_and_b32_e32 v23, 0xffff0000, v76
	v_lshlrev_b32_e32 v24, 16, v77
	v_and_b32_e32 v25, 0xffff0000, v77
	v_lshlrev_b32_e32 v26, 16, v78
	v_and_b32_e32 v27, 0xffff0000, v78
	v_lshlrev_b32_e32 v28, 16, v79
	v_and_b32_e32 v29, 0xffff0000, v79
	v_mul_f32_e32 v30, v23, v23
	v_mul_f32_e32 v31, v25, v25
	v_mul_f32_e32 v32, v27, v27
	v_mul_f32_e32 v33, v29, v29
	v_fmac_f32_e32 v30, v22, v22
	v_fmac_f32_e32 v31, v24, v24
	v_fmac_f32_e32 v32, v26, v26
	v_fmac_f32_e32 v33, v28, v28
	v_add_f32_e32 v120, v30, v31
	v_add_f32_e32 v120, v32, v120
	v_add_f32_e32 v120, v33, v120
	v_lshlrev_b32_e32 v22, 16, v80
	v_and_b32_e32 v23, 0xffff0000, v80
	v_lshlrev_b32_e32 v24, 16, v81
	v_and_b32_e32 v25, 0xffff0000, v81
	v_lshlrev_b32_e32 v26, 16, v82
	v_and_b32_e32 v27, 0xffff0000, v82
	v_lshlrev_b32_e32 v28, 16, v83
	v_and_b32_e32 v29, 0xffff0000, v83
	v_mul_f32_e32 v30, v23, v23
	v_mul_f32_e32 v31, v25, v25
	v_mul_f32_e32 v32, v27, v27
	v_mul_f32_e32 v33, v29, v29
	v_fmac_f32_e32 v30, v22, v22
	v_fmac_f32_e32 v31, v24, v24
	v_fmac_f32_e32 v32, v26, v26
	v_fmac_f32_e32 v33, v28, v28
	v_add_f32_e32 v128, v30, v31
	v_add_f32_e32 v128, v32, v128
	v_add_f32_e32 v128, v33, v128
	v_lshlrev_b32_e32 v22, 16, v84
	v_and_b32_e32 v23, 0xffff0000, v84
	v_lshlrev_b32_e32 v24, 16, v85
	v_and_b32_e32 v25, 0xffff0000, v85
	v_lshlrev_b32_e32 v26, 16, v86
	v_and_b32_e32 v27, 0xffff0000, v86
	v_lshlrev_b32_e32 v28, 16, v87
	v_and_b32_e32 v29, 0xffff0000, v87
	v_mul_f32_e32 v30, v23, v23
	v_mul_f32_e32 v31, v25, v25
	v_mul_f32_e32 v32, v27, v27
	v_mul_f32_e32 v33, v29, v29
	v_fmac_f32_e32 v30, v22, v22
	v_fmac_f32_e32 v31, v24, v24
	v_fmac_f32_e32 v32, v26, v26
	v_fmac_f32_e32 v33, v28, v28
	v_add_f32_e32 v121, v30, v31
	v_add_f32_e32 v121, v32, v121
	v_add_f32_e32 v121, v33, v121
	v_lshlrev_b32_e32 v22, 16, v88
	v_and_b32_e32 v23, 0xffff0000, v88
	v_lshlrev_b32_e32 v24, 16, v89
	v_and_b32_e32 v25, 0xffff0000, v89
	v_lshlrev_b32_e32 v26, 16, v90
	v_and_b32_e32 v27, 0xffff0000, v90
	v_lshlrev_b32_e32 v28, 16, v91
	v_and_b32_e32 v29, 0xffff0000, v91
	v_mul_f32_e32 v30, v23, v23
	v_mul_f32_e32 v31, v25, v25
	v_mul_f32_e32 v32, v27, v27
	v_mul_f32_e32 v33, v29, v29
	v_fmac_f32_e32 v30, v22, v22
	v_fmac_f32_e32 v31, v24, v24
	v_fmac_f32_e32 v32, v26, v26
	v_fmac_f32_e32 v33, v28, v28
	v_add_f32_e32 v129, v30, v31
	v_add_f32_e32 v129, v32, v129
	v_add_f32_e32 v129, v33, v129
	v_lshlrev_b32_e32 v22, 16, v92
	v_and_b32_e32 v23, 0xffff0000, v92
	v_lshlrev_b32_e32 v24, 16, v93
	v_and_b32_e32 v25, 0xffff0000, v93
	v_lshlrev_b32_e32 v26, 16, v94
	v_and_b32_e32 v27, 0xffff0000, v94
	v_lshlrev_b32_e32 v28, 16, v95
	v_and_b32_e32 v29, 0xffff0000, v95
	v_mul_f32_e32 v30, v23, v23
	v_mul_f32_e32 v31, v25, v25
	v_mul_f32_e32 v32, v27, v27
	v_mul_f32_e32 v33, v29, v29
	v_fmac_f32_e32 v30, v22, v22
	v_fmac_f32_e32 v31, v24, v24
	v_fmac_f32_e32 v32, v26, v26
	v_fmac_f32_e32 v33, v28, v28
	v_add_f32_e32 v122, v30, v31
	v_add_f32_e32 v122, v32, v122
	v_add_f32_e32 v122, v33, v122
	v_lshlrev_b32_e32 v22, 16, v96
	v_and_b32_e32 v23, 0xffff0000, v96
	v_lshlrev_b32_e32 v24, 16, v97
	v_and_b32_e32 v25, 0xffff0000, v97
	v_lshlrev_b32_e32 v26, 16, v98
	v_and_b32_e32 v27, 0xffff0000, v98
	v_lshlrev_b32_e32 v28, 16, v99
	v_and_b32_e32 v29, 0xffff0000, v99
	v_mul_f32_e32 v30, v23, v23
	v_mul_f32_e32 v31, v25, v25
	v_mul_f32_e32 v32, v27, v27
	v_mul_f32_e32 v33, v29, v29
	v_fmac_f32_e32 v30, v22, v22
	v_fmac_f32_e32 v31, v24, v24
	v_fmac_f32_e32 v32, v26, v26
	v_fmac_f32_e32 v33, v28, v28
	v_add_f32_e32 v130, v30, v31
	v_add_f32_e32 v130, v32, v130
	v_add_f32_e32 v130, v33, v130
	v_lshlrev_b32_e32 v22, 16, v100
	v_and_b32_e32 v23, 0xffff0000, v100
	v_lshlrev_b32_e32 v24, 16, v101
	v_and_b32_e32 v25, 0xffff0000, v101
	v_lshlrev_b32_e32 v26, 16, v102
	v_and_b32_e32 v27, 0xffff0000, v102
	v_lshlrev_b32_e32 v28, 16, v103
	v_and_b32_e32 v29, 0xffff0000, v103
	v_mul_f32_e32 v30, v23, v23
	v_mul_f32_e32 v31, v25, v25
	v_mul_f32_e32 v32, v27, v27
	v_mul_f32_e32 v33, v29, v29
	v_fmac_f32_e32 v30, v22, v22
	v_fmac_f32_e32 v31, v24, v24
	v_fmac_f32_e32 v32, v26, v26
	v_fmac_f32_e32 v33, v28, v28
	v_add_f32_e32 v123, v30, v31
	v_add_f32_e32 v123, v32, v123
	v_add_f32_e32 v123, v33, v123
	v_lshlrev_b32_e32 v22, 16, v104
	v_and_b32_e32 v23, 0xffff0000, v104
	v_lshlrev_b32_e32 v24, 16, v105
	v_and_b32_e32 v25, 0xffff0000, v105
	v_lshlrev_b32_e32 v26, 16, v106
	v_and_b32_e32 v27, 0xffff0000, v106
	v_lshlrev_b32_e32 v28, 16, v107
	v_and_b32_e32 v29, 0xffff0000, v107
	v_mul_f32_e32 v30, v23, v23
	v_mul_f32_e32 v31, v25, v25
	v_mul_f32_e32 v32, v27, v27
	v_mul_f32_e32 v33, v29, v29
	v_fmac_f32_e32 v30, v22, v22
	v_fmac_f32_e32 v31, v24, v24
	v_fmac_f32_e32 v32, v26, v26
	v_fmac_f32_e32 v33, v28, v28
	v_add_f32_e32 v131, v30, v31
	v_add_f32_e32 v131, v32, v131
	v_add_f32_e32 v131, v33, v131
	v_add_f32_dpp v116, v116, v116 quad_perm:[1,0,3,2] row_mask:0xf bank_mask:0xf bound_ctrl:1
	v_add_f32_dpp v117, v117, v117 quad_perm:[1,0,3,2] row_mask:0xf bank_mask:0xf bound_ctrl:1
	v_add_f32_dpp v118, v118, v118 quad_perm:[1,0,3,2] row_mask:0xf bank_mask:0xf bound_ctrl:1
	v_add_f32_dpp v119, v119, v119 quad_perm:[1,0,3,2] row_mask:0xf bank_mask:0xf bound_ctrl:1
	v_add_f32_dpp v120, v120, v120 quad_perm:[1,0,3,2] row_mask:0xf bank_mask:0xf bound_ctrl:1
	v_add_f32_dpp v121, v121, v121 quad_perm:[1,0,3,2] row_mask:0xf bank_mask:0xf bound_ctrl:1
	v_add_f32_dpp v122, v122, v122 quad_perm:[1,0,3,2] row_mask:0xf bank_mask:0xf bound_ctrl:1
	v_add_f32_dpp v123, v123, v123 quad_perm:[1,0,3,2] row_mask:0xf bank_mask:0xf bound_ctrl:1
	v_add_f32_dpp v124, v124, v124 quad_perm:[1,0,3,2] row_mask:0xf bank_mask:0xf bound_ctrl:1
	v_add_f32_dpp v125, v125, v125 quad_perm:[1,0,3,2] row_mask:0xf bank_mask:0xf bound_ctrl:1
	v_add_f32_dpp v126, v126, v126 quad_perm:[1,0,3,2] row_mask:0xf bank_mask:0xf bound_ctrl:1
	v_add_f32_dpp v127, v127, v127 quad_perm:[1,0,3,2] row_mask:0xf bank_mask:0xf bound_ctrl:1
	v_add_f32_dpp v128, v128, v128 quad_perm:[1,0,3,2] row_mask:0xf bank_mask:0xf bound_ctrl:1
	v_add_f32_dpp v129, v129, v129 quad_perm:[1,0,3,2] row_mask:0xf bank_mask:0xf bound_ctrl:1
	v_add_f32_dpp v130, v130, v130 quad_perm:[1,0,3,2] row_mask:0xf bank_mask:0xf bound_ctrl:1
	v_add_f32_dpp v131, v131, v131 quad_perm:[1,0,3,2] row_mask:0xf bank_mask:0xf bound_ctrl:1
	v_add_f32_dpp v116, v116, v116 quad_perm:[2,3,0,1] row_mask:0xf bank_mask:0xf bound_ctrl:1
	v_add_f32_dpp v117, v117, v117 quad_perm:[2,3,0,1] row_mask:0xf bank_mask:0xf bound_ctrl:1
	v_add_f32_dpp v118, v118, v118 quad_perm:[2,3,0,1] row_mask:0xf bank_mask:0xf bound_ctrl:1
	v_add_f32_dpp v119, v119, v119 quad_perm:[2,3,0,1] row_mask:0xf bank_mask:0xf bound_ctrl:1
	v_add_f32_dpp v120, v120, v120 quad_perm:[2,3,0,1] row_mask:0xf bank_mask:0xf bound_ctrl:1
	v_add_f32_dpp v121, v121, v121 quad_perm:[2,3,0,1] row_mask:0xf bank_mask:0xf bound_ctrl:1
	v_add_f32_dpp v122, v122, v122 quad_perm:[2,3,0,1] row_mask:0xf bank_mask:0xf bound_ctrl:1
	v_add_f32_dpp v123, v123, v123 quad_perm:[2,3,0,1] row_mask:0xf bank_mask:0xf bound_ctrl:1
	v_add_f32_dpp v124, v124, v124 quad_perm:[2,3,0,1] row_mask:0xf bank_mask:0xf bound_ctrl:1
	v_add_f32_dpp v125, v125, v125 quad_perm:[2,3,0,1] row_mask:0xf bank_mask:0xf bound_ctrl:1
	v_add_f32_dpp v126, v126, v126 quad_perm:[2,3,0,1] row_mask:0xf bank_mask:0xf bound_ctrl:1
	v_add_f32_dpp v127, v127, v127 quad_perm:[2,3,0,1] row_mask:0xf bank_mask:0xf bound_ctrl:1
	v_add_f32_dpp v128, v128, v128 quad_perm:[2,3,0,1] row_mask:0xf bank_mask:0xf bound_ctrl:1
	v_add_f32_dpp v129, v129, v129 quad_perm:[2,3,0,1] row_mask:0xf bank_mask:0xf bound_ctrl:1
	v_add_f32_dpp v130, v130, v130 quad_perm:[2,3,0,1] row_mask:0xf bank_mask:0xf bound_ctrl:1
	v_add_f32_dpp v131, v131, v131 quad_perm:[2,3,0,1] row_mask:0xf bank_mask:0xf bound_ctrl:1
	ds_bpermute_b32 v132, v6, v116
	ds_bpermute_b32 v133, v6, v117
	ds_bpermute_b32 v134, v6, v118
	ds_bpermute_b32 v135, v6, v119
	ds_bpermute_b32 v136, v6, v120
	ds_bpermute_b32 v137, v6, v121
	ds_bpermute_b32 v138, v6, v122
	ds_bpermute_b32 v139, v6, v123
	s_waitcnt lgkmcnt(0)
	v_add_f32_e32 v116, v116, v132
	v_add_f32_e32 v117, v117, v133
	v_add_f32_e32 v118, v118, v134
	v_add_f32_e32 v119, v119, v135
	v_add_f32_e32 v120, v120, v136
	v_add_f32_e32 v121, v121, v137
	v_add_f32_e32 v122, v122, v138
	v_add_f32_e32 v123, v123, v139
	ds_bpermute_b32 v132, v6, v124
	ds_bpermute_b32 v133, v6, v125
	ds_bpermute_b32 v134, v6, v126
	ds_bpermute_b32 v135, v6, v127
	ds_bpermute_b32 v136, v6, v128
	ds_bpermute_b32 v137, v6, v129
	ds_bpermute_b32 v138, v6, v130
	ds_bpermute_b32 v139, v6, v131
	s_waitcnt lgkmcnt(0)
	v_add_f32_e32 v124, v124, v132
	v_add_f32_e32 v125, v125, v133
	v_add_f32_e32 v126, v126, v134
	v_add_f32_e32 v127, v127, v135
	v_add_f32_e32 v128, v128, v136
	v_add_f32_e32 v129, v129, v137
	v_add_f32_e32 v130, v130, v138
	v_add_f32_e32 v131, v131, v139
	v_fmamk_f32 v116, v116, 0x3c800000, v198
	v_fmamk_f32 v117, v117, 0x3c800000, v198
	v_fmamk_f32 v118, v118, 0x3c800000, v198
	v_fmamk_f32 v119, v119, 0x3c800000, v198
	v_fmamk_f32 v120, v120, 0x3c800000, v198
	v_fmamk_f32 v121, v121, 0x3c800000, v198
	v_fmamk_f32 v122, v122, 0x3c800000, v198
	v_fmamk_f32 v123, v123, 0x3c800000, v198
	v_fmamk_f32 v124, v124, 0x3c800000, v198
	v_fmamk_f32 v125, v125, 0x3c800000, v198
	v_fmamk_f32 v126, v126, 0x3c800000, v198
	v_fmamk_f32 v127, v127, 0x3c800000, v198
	v_fmamk_f32 v128, v128, 0x3c800000, v198
	v_fmamk_f32 v129, v129, 0x3c800000, v198
	v_fmamk_f32 v130, v130, 0x3c800000, v198
	v_fmamk_f32 v131, v131, 0x3c800000, v198
	v_rsq_f32_e32 v116, v116
	v_rsq_f32_e32 v117, v117
	v_rsq_f32_e32 v118, v118
	v_rsq_f32_e32 v119, v119
	v_rsq_f32_e32 v120, v120
	v_rsq_f32_e32 v121, v121
	v_rsq_f32_e32 v122, v122
	v_rsq_f32_e32 v123, v123
	v_rsq_f32_e32 v124, v124
	v_rsq_f32_e32 v125, v125
	v_rsq_f32_e32 v126, v126
	v_rsq_f32_e32 v127, v127
	v_rsq_f32_e32 v128, v128
	v_rsq_f32_e32 v129, v129
	v_rsq_f32_e32 v130, v130
	v_rsq_f32_e32 v131, v131
	v_mul_f32_e32 v116, 0x3e38aa3b, v116
	v_mul_f32_e32 v117, 0x3e38aa3b, v117
	v_mul_f32_e32 v118, 0x3e38aa3b, v118
	v_mul_f32_e32 v119, 0x3e38aa3b, v119
	v_mul_f32_e32 v120, 0x3e38aa3b, v120
	v_mul_f32_e32 v121, 0x3e38aa3b, v121
	v_mul_f32_e32 v122, 0x3e38aa3b, v122
	v_mul_f32_e32 v123, 0x3e38aa3b, v123
	v_lshlrev_b32_e32 v22, 16, v44
	v_and_b32_e32 v23, 0xffff0000, v44
	v_lshlrev_b32_e32 v24, 16, v45
	v_and_b32_e32 v25, 0xffff0000, v45
	v_lshlrev_b32_e32 v26, 16, v46
	v_and_b32_e32 v27, 0xffff0000, v46
	v_lshlrev_b32_e32 v28, 16, v47
	v_and_b32_e32 v29, 0xffff0000, v47
	v_mov_b32_e32 v38, v116
	v_pk_mul_f32 v[30:31], v[212:213], v[22:23]
	v_pk_mul_f32 v[32:33], v[214:215], v[24:25]
	v_pk_mul_f32 v[34:35], v[216:217], v[26:27]
	v_pk_mul_f32 v[36:37], v[218:219], v[28:29]
	v_pk_mul_f32 v[30:31], v[30:31], v[38:39] op_sel_hi:[1,0]
	v_pk_mul_f32 v[32:33], v[32:33], v[38:39] op_sel_hi:[1,0]
	v_pk_mul_f32 v[34:35], v[34:35], v[38:39] op_sel_hi:[1,0]
	v_pk_mul_f32 v[36:37], v[36:37], v[38:39] op_sel_hi:[1,0]
	v_cvt_pk_bf16_f32 v44, v30, v31
	v_cvt_pk_bf16_f32 v45, v32, v33
	v_cvt_pk_bf16_f32 v46, v34, v35
	v_cvt_pk_bf16_f32 v47, v36, v37
	global_store_dwordx4 v108, v[44:47], s[36:37] offset:2048
	v_lshlrev_b32_e32 v22, 16, v48
	v_and_b32_e32 v23, 0xffff0000, v48
	v_lshlrev_b32_e32 v24, 16, v49
	v_and_b32_e32 v25, 0xffff0000, v49
	v_lshlrev_b32_e32 v26, 16, v50
	v_and_b32_e32 v27, 0xffff0000, v50
	v_lshlrev_b32_e32 v28, 16, v51
	v_and_b32_e32 v29, 0xffff0000, v51
	v_mov_b32_e32 v38, v124
	v_pk_mul_f32 v[30:31], v[220:221], v[22:23]
	v_pk_mul_f32 v[32:33], v[222:223], v[24:25]
	v_pk_mul_f32 v[34:35], v[224:225], v[26:27]
	v_pk_mul_f32 v[36:37], v[226:227], v[28:29]
	v_pk_mul_f32 v[30:31], v[30:31], v[38:39] op_sel_hi:[1,0]
	v_pk_mul_f32 v[32:33], v[32:33], v[38:39] op_sel_hi:[1,0]
	v_pk_mul_f32 v[34:35], v[34:35], v[38:39] op_sel_hi:[1,0]
	v_pk_mul_f32 v[36:37], v[36:37], v[38:39] op_sel_hi:[1,0]
	v_cvt_pk_bf16_f32 v48, v30, v31
	v_cvt_pk_bf16_f32 v49, v32, v33
	v_cvt_pk_bf16_f32 v50, v34, v35
	v_cvt_pk_bf16_f32 v51, v36, v37
	global_store_dwordx4 v108, v[48:51], s[36:37] offset:2560
	v_lshlrev_b32_e32 v22, 16, v52
	v_and_b32_e32 v23, 0xffff0000, v52
	v_lshlrev_b32_e32 v24, 16, v53
	v_and_b32_e32 v25, 0xffff0000, v53
	v_lshlrev_b32_e32 v26, 16, v54
	v_and_b32_e32 v27, 0xffff0000, v54
	v_lshlrev_b32_e32 v28, 16, v55
	v_and_b32_e32 v29, 0xffff0000, v55
	v_mov_b32_e32 v38, v117
	v_pk_mul_f32 v[30:31], v[212:213], v[22:23]
	v_pk_mul_f32 v[32:33], v[214:215], v[24:25]
	v_pk_mul_f32 v[34:35], v[216:217], v[26:27]
	v_pk_mul_f32 v[36:37], v[218:219], v[28:29]
	v_pk_mul_f32 v[30:31], v[30:31], v[38:39] op_sel_hi:[1,0]
	v_pk_mul_f32 v[32:33], v[32:33], v[38:39] op_sel_hi:[1,0]
	v_pk_mul_f32 v[34:35], v[34:35], v[38:39] op_sel_hi:[1,0]
	v_pk_mul_f32 v[36:37], v[36:37], v[38:39] op_sel_hi:[1,0]
	v_cvt_pk_bf16_f32 v52, v30, v31
	v_cvt_pk_bf16_f32 v53, v32, v33
	v_cvt_pk_bf16_f32 v54, v34, v35
	v_cvt_pk_bf16_f32 v55, v36, v37
	global_store_dwordx4 v109, v[52:55], s[36:37] offset:2048
	v_lshlrev_b32_e32 v22, 16, v56
	v_and_b32_e32 v23, 0xffff0000, v56
	v_lshlrev_b32_e32 v24, 16, v57
	v_and_b32_e32 v25, 0xffff0000, v57
	v_lshlrev_b32_e32 v26, 16, v58
	v_and_b32_e32 v27, 0xffff0000, v58
	v_lshlrev_b32_e32 v28, 16, v59
	v_and_b32_e32 v29, 0xffff0000, v59
	v_mov_b32_e32 v38, v125
	v_pk_mul_f32 v[30:31], v[220:221], v[22:23]
	v_pk_mul_f32 v[32:33], v[222:223], v[24:25]
	v_pk_mul_f32 v[34:35], v[224:225], v[26:27]
	v_pk_mul_f32 v[36:37], v[226:227], v[28:29]
	v_pk_mul_f32 v[30:31], v[30:31], v[38:39] op_sel_hi:[1,0]
	v_pk_mul_f32 v[32:33], v[32:33], v[38:39] op_sel_hi:[1,0]
	v_pk_mul_f32 v[34:35], v[34:35], v[38:39] op_sel_hi:[1,0]
	v_pk_mul_f32 v[36:37], v[36:37], v[38:39] op_sel_hi:[1,0]
	v_cvt_pk_bf16_f32 v56, v30, v31
	v_cvt_pk_bf16_f32 v57, v32, v33
	v_cvt_pk_bf16_f32 v58, v34, v35
	v_cvt_pk_bf16_f32 v59, v36, v37
	global_store_dwordx4 v109, v[56:59], s[36:37] offset:2560
	v_lshlrev_b32_e32 v22, 16, v60
	v_and_b32_e32 v23, 0xffff0000, v60
	v_lshlrev_b32_e32 v24, 16, v61
	v_and_b32_e32 v25, 0xffff0000, v61
	v_lshlrev_b32_e32 v26, 16, v62
	v_and_b32_e32 v27, 0xffff0000, v62
	v_lshlrev_b32_e32 v28, 16, v63
	v_and_b32_e32 v29, 0xffff0000, v63
	v_mov_b32_e32 v38, v118
	v_pk_mul_f32 v[30:31], v[212:213], v[22:23]
	v_pk_mul_f32 v[32:33], v[214:215], v[24:25]
	v_pk_mul_f32 v[34:35], v[216:217], v[26:27]
	v_pk_mul_f32 v[36:37], v[218:219], v[28:29]
	v_pk_mul_f32 v[30:31], v[30:31], v[38:39] op_sel_hi:[1,0]
	v_pk_mul_f32 v[32:33], v[32:33], v[38:39] op_sel_hi:[1,0]
	v_pk_mul_f32 v[34:35], v[34:35], v[38:39] op_sel_hi:[1,0]
	v_pk_mul_f32 v[36:37], v[36:37], v[38:39] op_sel_hi:[1,0]
	v_cvt_pk_bf16_f32 v60, v30, v31
	v_cvt_pk_bf16_f32 v61, v32, v33
	v_cvt_pk_bf16_f32 v62, v34, v35
	v_cvt_pk_bf16_f32 v63, v36, v37
	global_store_dwordx4 v110, v[60:63], s[36:37] offset:2048
	v_lshlrev_b32_e32 v22, 16, v64
	v_and_b32_e32 v23, 0xffff0000, v64
	v_lshlrev_b32_e32 v24, 16, v65
	v_and_b32_e32 v25, 0xffff0000, v65
	v_lshlrev_b32_e32 v26, 16, v66
	v_and_b32_e32 v27, 0xffff0000, v66
	v_lshlrev_b32_e32 v28, 16, v67
	v_and_b32_e32 v29, 0xffff0000, v67
	v_mov_b32_e32 v38, v126
	v_pk_mul_f32 v[30:31], v[220:221], v[22:23]
	v_pk_mul_f32 v[32:33], v[222:223], v[24:25]
	v_pk_mul_f32 v[34:35], v[224:225], v[26:27]
	v_pk_mul_f32 v[36:37], v[226:227], v[28:29]
	v_pk_mul_f32 v[30:31], v[30:31], v[38:39] op_sel_hi:[1,0]
	v_pk_mul_f32 v[32:33], v[32:33], v[38:39] op_sel_hi:[1,0]
	v_pk_mul_f32 v[34:35], v[34:35], v[38:39] op_sel_hi:[1,0]
	v_pk_mul_f32 v[36:37], v[36:37], v[38:39] op_sel_hi:[1,0]
	v_cvt_pk_bf16_f32 v64, v30, v31
	v_cvt_pk_bf16_f32 v65, v32, v33
	v_cvt_pk_bf16_f32 v66, v34, v35
	v_cvt_pk_bf16_f32 v67, v36, v37
	global_store_dwordx4 v110, v[64:67], s[36:37] offset:2560
	v_lshlrev_b32_e32 v22, 16, v68
	v_and_b32_e32 v23, 0xffff0000, v68
	v_lshlrev_b32_e32 v24, 16, v69
	v_and_b32_e32 v25, 0xffff0000, v69
	v_lshlrev_b32_e32 v26, 16, v70
	v_and_b32_e32 v27, 0xffff0000, v70
	v_lshlrev_b32_e32 v28, 16, v71
	v_and_b32_e32 v29, 0xffff0000, v71
	v_mov_b32_e32 v38, v119
	v_pk_mul_f32 v[30:31], v[212:213], v[22:23]
	v_pk_mul_f32 v[32:33], v[214:215], v[24:25]
	v_pk_mul_f32 v[34:35], v[216:217], v[26:27]
	v_pk_mul_f32 v[36:37], v[218:219], v[28:29]
	v_pk_mul_f32 v[30:31], v[30:31], v[38:39] op_sel_hi:[1,0]
	v_pk_mul_f32 v[32:33], v[32:33], v[38:39] op_sel_hi:[1,0]
	v_pk_mul_f32 v[34:35], v[34:35], v[38:39] op_sel_hi:[1,0]
	v_pk_mul_f32 v[36:37], v[36:37], v[38:39] op_sel_hi:[1,0]
	v_cvt_pk_bf16_f32 v68, v30, v31
	v_cvt_pk_bf16_f32 v69, v32, v33
	v_cvt_pk_bf16_f32 v70, v34, v35
	v_cvt_pk_bf16_f32 v71, v36, v37
	global_store_dwordx4 v111, v[68:71], s[36:37] offset:2048
	v_lshlrev_b32_e32 v22, 16, v72
	v_and_b32_e32 v23, 0xffff0000, v72
	v_lshlrev_b32_e32 v24, 16, v73
	v_and_b32_e32 v25, 0xffff0000, v73
	v_lshlrev_b32_e32 v26, 16, v74
	v_and_b32_e32 v27, 0xffff0000, v74
	v_lshlrev_b32_e32 v28, 16, v75
	v_and_b32_e32 v29, 0xffff0000, v75
	v_mov_b32_e32 v38, v127
	v_pk_mul_f32 v[30:31], v[220:221], v[22:23]
	v_pk_mul_f32 v[32:33], v[222:223], v[24:25]
	v_pk_mul_f32 v[34:35], v[224:225], v[26:27]
	v_pk_mul_f32 v[36:37], v[226:227], v[28:29]
	v_pk_mul_f32 v[30:31], v[30:31], v[38:39] op_sel_hi:[1,0]
	v_pk_mul_f32 v[32:33], v[32:33], v[38:39] op_sel_hi:[1,0]
	v_pk_mul_f32 v[34:35], v[34:35], v[38:39] op_sel_hi:[1,0]
	v_pk_mul_f32 v[36:37], v[36:37], v[38:39] op_sel_hi:[1,0]
	v_cvt_pk_bf16_f32 v72, v30, v31
	v_cvt_pk_bf16_f32 v73, v32, v33
	v_cvt_pk_bf16_f32 v74, v34, v35
	v_cvt_pk_bf16_f32 v75, v36, v37
	global_store_dwordx4 v111, v[72:75], s[36:37] offset:2560
	v_lshlrev_b32_e32 v22, 16, v76
	v_and_b32_e32 v23, 0xffff0000, v76
	v_lshlrev_b32_e32 v24, 16, v77
	v_and_b32_e32 v25, 0xffff0000, v77
	v_lshlrev_b32_e32 v26, 16, v78
	v_and_b32_e32 v27, 0xffff0000, v78
	v_lshlrev_b32_e32 v28, 16, v79
	v_and_b32_e32 v29, 0xffff0000, v79
	v_mov_b32_e32 v38, v120
	v_pk_mul_f32 v[30:31], v[212:213], v[22:23]
	v_pk_mul_f32 v[32:33], v[214:215], v[24:25]
	v_pk_mul_f32 v[34:35], v[216:217], v[26:27]
	v_pk_mul_f32 v[36:37], v[218:219], v[28:29]
	v_pk_mul_f32 v[30:31], v[30:31], v[38:39] op_sel_hi:[1,0]
	v_pk_mul_f32 v[32:33], v[32:33], v[38:39] op_sel_hi:[1,0]
	v_pk_mul_f32 v[34:35], v[34:35], v[38:39] op_sel_hi:[1,0]
	v_pk_mul_f32 v[36:37], v[36:37], v[38:39] op_sel_hi:[1,0]
	v_cvt_pk_bf16_f32 v76, v30, v31
	v_cvt_pk_bf16_f32 v77, v32, v33
	v_cvt_pk_bf16_f32 v78, v34, v35
	v_cvt_pk_bf16_f32 v79, v36, v37
	global_store_dwordx4 v112, v[76:79], s[36:37] offset:2048
	v_lshlrev_b32_e32 v22, 16, v80
	v_and_b32_e32 v23, 0xffff0000, v80
	v_lshlrev_b32_e32 v24, 16, v81
	v_and_b32_e32 v25, 0xffff0000, v81
	v_lshlrev_b32_e32 v26, 16, v82
	v_and_b32_e32 v27, 0xffff0000, v82
	v_lshlrev_b32_e32 v28, 16, v83
	v_and_b32_e32 v29, 0xffff0000, v83
	v_mov_b32_e32 v38, v128
	v_pk_mul_f32 v[30:31], v[220:221], v[22:23]
	v_pk_mul_f32 v[32:33], v[222:223], v[24:25]
	v_pk_mul_f32 v[34:35], v[224:225], v[26:27]
	v_pk_mul_f32 v[36:37], v[226:227], v[28:29]
	v_pk_mul_f32 v[30:31], v[30:31], v[38:39] op_sel_hi:[1,0]
	v_pk_mul_f32 v[32:33], v[32:33], v[38:39] op_sel_hi:[1,0]
	v_pk_mul_f32 v[34:35], v[34:35], v[38:39] op_sel_hi:[1,0]
	v_pk_mul_f32 v[36:37], v[36:37], v[38:39] op_sel_hi:[1,0]
	v_cvt_pk_bf16_f32 v80, v30, v31
	v_cvt_pk_bf16_f32 v81, v32, v33
	v_cvt_pk_bf16_f32 v82, v34, v35
	v_cvt_pk_bf16_f32 v83, v36, v37
	global_store_dwordx4 v112, v[80:83], s[36:37] offset:2560
	v_lshlrev_b32_e32 v22, 16, v84
	v_and_b32_e32 v23, 0xffff0000, v84
	v_lshlrev_b32_e32 v24, 16, v85
	v_and_b32_e32 v25, 0xffff0000, v85
	v_lshlrev_b32_e32 v26, 16, v86
	v_and_b32_e32 v27, 0xffff0000, v86
	v_lshlrev_b32_e32 v28, 16, v87
	v_and_b32_e32 v29, 0xffff0000, v87
	v_mov_b32_e32 v38, v121
	v_pk_mul_f32 v[30:31], v[212:213], v[22:23]
	v_pk_mul_f32 v[32:33], v[214:215], v[24:25]
	v_pk_mul_f32 v[34:35], v[216:217], v[26:27]
	v_pk_mul_f32 v[36:37], v[218:219], v[28:29]
	v_pk_mul_f32 v[30:31], v[30:31], v[38:39] op_sel_hi:[1,0]
	v_pk_mul_f32 v[32:33], v[32:33], v[38:39] op_sel_hi:[1,0]
	v_pk_mul_f32 v[34:35], v[34:35], v[38:39] op_sel_hi:[1,0]
	v_pk_mul_f32 v[36:37], v[36:37], v[38:39] op_sel_hi:[1,0]
	v_cvt_pk_bf16_f32 v84, v30, v31
	v_cvt_pk_bf16_f32 v85, v32, v33
	v_cvt_pk_bf16_f32 v86, v34, v35
	v_cvt_pk_bf16_f32 v87, v36, v37
	global_store_dwordx4 v113, v[84:87], s[36:37] offset:2048
	v_lshlrev_b32_e32 v22, 16, v88
	v_and_b32_e32 v23, 0xffff0000, v88
	v_lshlrev_b32_e32 v24, 16, v89
	v_and_b32_e32 v25, 0xffff0000, v89
	v_lshlrev_b32_e32 v26, 16, v90
	v_and_b32_e32 v27, 0xffff0000, v90
	v_lshlrev_b32_e32 v28, 16, v91
	v_and_b32_e32 v29, 0xffff0000, v91
	v_mov_b32_e32 v38, v129
	v_pk_mul_f32 v[30:31], v[220:221], v[22:23]
	v_pk_mul_f32 v[32:33], v[222:223], v[24:25]
	v_pk_mul_f32 v[34:35], v[224:225], v[26:27]
	v_pk_mul_f32 v[36:37], v[226:227], v[28:29]
	v_pk_mul_f32 v[30:31], v[30:31], v[38:39] op_sel_hi:[1,0]
	v_pk_mul_f32 v[32:33], v[32:33], v[38:39] op_sel_hi:[1,0]
	v_pk_mul_f32 v[34:35], v[34:35], v[38:39] op_sel_hi:[1,0]
	v_pk_mul_f32 v[36:37], v[36:37], v[38:39] op_sel_hi:[1,0]
	v_cvt_pk_bf16_f32 v88, v30, v31
	v_cvt_pk_bf16_f32 v89, v32, v33
	v_cvt_pk_bf16_f32 v90, v34, v35
	v_cvt_pk_bf16_f32 v91, v36, v37
	global_store_dwordx4 v113, v[88:91], s[36:37] offset:2560
	v_lshlrev_b32_e32 v22, 16, v92
	v_and_b32_e32 v23, 0xffff0000, v92
	v_lshlrev_b32_e32 v24, 16, v93
	v_and_b32_e32 v25, 0xffff0000, v93
	v_lshlrev_b32_e32 v26, 16, v94
	v_and_b32_e32 v27, 0xffff0000, v94
	v_lshlrev_b32_e32 v28, 16, v95
	v_and_b32_e32 v29, 0xffff0000, v95
	v_mov_b32_e32 v38, v122
	v_pk_mul_f32 v[30:31], v[212:213], v[22:23]
	v_pk_mul_f32 v[32:33], v[214:215], v[24:25]
	v_pk_mul_f32 v[34:35], v[216:217], v[26:27]
	v_pk_mul_f32 v[36:37], v[218:219], v[28:29]
	v_pk_mul_f32 v[30:31], v[30:31], v[38:39] op_sel_hi:[1,0]
	v_pk_mul_f32 v[32:33], v[32:33], v[38:39] op_sel_hi:[1,0]
	v_pk_mul_f32 v[34:35], v[34:35], v[38:39] op_sel_hi:[1,0]
	v_pk_mul_f32 v[36:37], v[36:37], v[38:39] op_sel_hi:[1,0]
	v_cvt_pk_bf16_f32 v92, v30, v31
	v_cvt_pk_bf16_f32 v93, v32, v33
	v_cvt_pk_bf16_f32 v94, v34, v35
	v_cvt_pk_bf16_f32 v95, v36, v37
	global_store_dwordx4 v114, v[92:95], s[36:37] offset:2048
	v_lshlrev_b32_e32 v22, 16, v96
	v_and_b32_e32 v23, 0xffff0000, v96
	v_lshlrev_b32_e32 v24, 16, v97
	v_and_b32_e32 v25, 0xffff0000, v97
	v_lshlrev_b32_e32 v26, 16, v98
	v_and_b32_e32 v27, 0xffff0000, v98
	v_lshlrev_b32_e32 v28, 16, v99
	v_and_b32_e32 v29, 0xffff0000, v99
	v_mov_b32_e32 v38, v130
	v_pk_mul_f32 v[30:31], v[220:221], v[22:23]
	v_pk_mul_f32 v[32:33], v[222:223], v[24:25]
	v_pk_mul_f32 v[34:35], v[224:225], v[26:27]
	v_pk_mul_f32 v[36:37], v[226:227], v[28:29]
	v_pk_mul_f32 v[30:31], v[30:31], v[38:39] op_sel_hi:[1,0]
	v_pk_mul_f32 v[32:33], v[32:33], v[38:39] op_sel_hi:[1,0]
	v_pk_mul_f32 v[34:35], v[34:35], v[38:39] op_sel_hi:[1,0]
	v_pk_mul_f32 v[36:37], v[36:37], v[38:39] op_sel_hi:[1,0]
	v_cvt_pk_bf16_f32 v96, v30, v31
	v_cvt_pk_bf16_f32 v97, v32, v33
	v_cvt_pk_bf16_f32 v98, v34, v35
	v_cvt_pk_bf16_f32 v99, v36, v37
	global_store_dwordx4 v114, v[96:99], s[36:37] offset:2560
	v_lshlrev_b32_e32 v22, 16, v100
	v_and_b32_e32 v23, 0xffff0000, v100
	v_lshlrev_b32_e32 v24, 16, v101
	v_and_b32_e32 v25, 0xffff0000, v101
	v_lshlrev_b32_e32 v26, 16, v102
	v_and_b32_e32 v27, 0xffff0000, v102
	v_lshlrev_b32_e32 v28, 16, v103
	v_and_b32_e32 v29, 0xffff0000, v103
	v_mov_b32_e32 v38, v123
	v_pk_mul_f32 v[30:31], v[212:213], v[22:23]
	v_pk_mul_f32 v[32:33], v[214:215], v[24:25]
	v_pk_mul_f32 v[34:35], v[216:217], v[26:27]
	v_pk_mul_f32 v[36:37], v[218:219], v[28:29]
	v_pk_mul_f32 v[30:31], v[30:31], v[38:39] op_sel_hi:[1,0]
	v_pk_mul_f32 v[32:33], v[32:33], v[38:39] op_sel_hi:[1,0]
	v_pk_mul_f32 v[34:35], v[34:35], v[38:39] op_sel_hi:[1,0]
	v_pk_mul_f32 v[36:37], v[36:37], v[38:39] op_sel_hi:[1,0]
	v_cvt_pk_bf16_f32 v100, v30, v31
	v_cvt_pk_bf16_f32 v101, v32, v33
	v_cvt_pk_bf16_f32 v102, v34, v35
	v_cvt_pk_bf16_f32 v103, v36, v37
	global_store_dwordx4 v115, v[100:103], s[36:37] offset:2048
	v_lshlrev_b32_e32 v22, 16, v104
	v_and_b32_e32 v23, 0xffff0000, v104
	v_lshlrev_b32_e32 v24, 16, v105
	v_and_b32_e32 v25, 0xffff0000, v105
	v_lshlrev_b32_e32 v26, 16, v106
	v_and_b32_e32 v27, 0xffff0000, v106
	v_lshlrev_b32_e32 v28, 16, v107
	v_and_b32_e32 v29, 0xffff0000, v107
	v_mov_b32_e32 v38, v131
	v_pk_mul_f32 v[30:31], v[220:221], v[22:23]
	v_pk_mul_f32 v[32:33], v[222:223], v[24:25]
	v_pk_mul_f32 v[34:35], v[224:225], v[26:27]
	v_pk_mul_f32 v[36:37], v[226:227], v[28:29]
	v_pk_mul_f32 v[30:31], v[30:31], v[38:39] op_sel_hi:[1,0]
	v_pk_mul_f32 v[32:33], v[32:33], v[38:39] op_sel_hi:[1,0]
	v_pk_mul_f32 v[34:35], v[34:35], v[38:39] op_sel_hi:[1,0]
	v_pk_mul_f32 v[36:37], v[36:37], v[38:39] op_sel_hi:[1,0]
	v_cvt_pk_bf16_f32 v104, v30, v31
	v_cvt_pk_bf16_f32 v105, v32, v33
	v_cvt_pk_bf16_f32 v106, v34, v35
	v_cvt_pk_bf16_f32 v107, v36, v37
	global_store_dwordx4 v115, v[104:107], s[36:37] offset:2560
	s_mov_b64 s[2:3], exec

.LBB0_263:
	v_mov_b32_e32 v0, v196
	s_and_b64 vcc, exec, s[38:39]
	s_cbranch_vccnz .LBB0_270
	v_lshrrev_b32_e32 v2, 3, v0
	v_and_b32_e32 v3, 7, v0
	v_mul_u32_u24_e64 v4, v2, s75
	v_mul_u32_u24_e32 v5, 0x90, v2
	v_mul_u32_u24_e32 v6, 0x480, v3
	v_lshlrev_b32_e32 v7, 14, v2
	v_lshl_add_u32 v4, v3, 4, v4
	v_lshl_add_u32 v5, v3, 4, v5
	v_lshl_add_u32 v6, v2, 1, v6
	v_lshl_add_u32 v7, v3, 4, v7
	s_lshr_b32 s0, s22, 7
	s_and_b32 s1, s22, 0x7f
	s_lshl_b32 s2, s1, 6
	s_add_i32 s3, s0, 0
	s_lshr_b32 s4, s3, 2
	s_and_b32 s5, s3, 3
	s_lshl_b32 s4, s4, 13
	s_add_i32 s4, s4, s2
	s_mul_i32 s4, s4, 0x1e00
	s_lshl_b32 s5, s5, 7
	s_add_i32 s4, s4, s5
	s_add_u32 s6, s36, s4
	s_addc_u32 s7, s37, 0
	global_load_dwordx4 v[44:47], v4, s[6:7] offset:3072 nt
	s_add_i32 s3, s0, 2
	s_lshr_b32 s4, s3, 2
	s_and_b32 s5, s3, 3
	s_lshl_b32 s4, s4, 13
	s_add_i32 s4, s4, s2
	s_mul_i32 s4, s4, 0x1e00
	s_lshl_b32 s5, s5, 7
	s_add_i32 s4, s4, s5
	s_add_u32 s6, s36, s4
	s_addc_u32 s7, s37, 0
	global_load_dwordx4 v[48:51], v4, s[6:7] offset:3072 nt
	s_add_i32 s3, s0, 4
	s_lshr_b32 s4, s3, 2
	s_and_b32 s5, s3, 3
	s_lshl_b32 s4, s4, 13
	s_add_i32 s4, s4, s2
	s_mul_i32 s4, s4, 0x1e00
	s_lshl_b32 s5, s5, 7
	s_add_i32 s4, s4, s5
	s_add_u32 s6, s36, s4
	s_addc_u32 s7, s37, 0
	global_load_dwordx4 v[52:55], v4, s[6:7] offset:3072 nt
	s_add_i32 s3, s0, 6
	s_lshr_b32 s4, s3, 2
	s_and_b32 s5, s3, 3
	s_lshl_b32 s4, s4, 13
	s_add_i32 s4, s4, s2
	s_mul_i32 s4, s4, 0x1e00
	s_lshl_b32 s5, s5, 7
	s_add_i32 s4, s4, s5
	s_add_u32 s6, s36, s4
	s_addc_u32 s7, s37, 0
	global_load_dwordx4 v[56:59], v4, s[6:7] offset:3072 nt
	s_add_i32 s3, s0, 8
	s_lshr_b32 s4, s3, 2
	s_and_b32 s5, s3, 3
	s_lshl_b32 s4, s4, 13
	s_add_i32 s4, s4, s2
	s_mul_i32 s4, s4, 0x1e00
	s_lshl_b32 s5, s5, 7
	s_add_i32 s4, s4, s5
	s_add_u32 s6, s36, s4
	s_addc_u32 s7, s37, 0
	global_load_dwordx4 v[60:63], v4, s[6:7] offset:3072 nt
	s_add_i32 s3, s0, 10
	s_lshr_b32 s4, s3, 2
	s_and_b32 s5, s3, 3
	s_lshl_b32 s4, s4, 13
	s_add_i32 s4, s4, s2
	s_mul_i32 s4, s4, 0x1e00
	s_lshl_b32 s5, s5, 7
	s_add_i32 s4, s4, s5
	s_add_u32 s6, s36, s4
	s_addc_u32 s7, s37, 0
	global_load_dwordx4 v[64:67], v4, s[6:7] offset:3072 nt
	s_add_i32 s3, s0, 12
	s_lshr_b32 s4, s3, 2
	s_and_b32 s5, s3, 3
	s_lshl_b32 s4, s4, 13
	s_add_i32 s4, s4, s2
	s_mul_i32 s4, s4, 0x1e00
	s_lshl_b32 s5, s5, 7
	s_add_i32 s4, s4, s5
	s_add_u32 s6, s36, s4
	s_addc_u32 s7, s37, 0
	global_load_dwordx4 v[68:71], v4, s[6:7] offset:3072 nt
	s_add_i32 s3, s0, 14
	s_lshr_b32 s4, s3, 2
	s_and_b32 s5, s3, 3
	s_lshl_b32 s4, s4, 13
	s_add_i32 s4, s4, s2
	s_mul_i32 s4, s4, 0x1e00
	s_lshl_b32 s5, s5, 7
	s_add_i32 s4, s4, s5
	s_add_u32 s6, s36, s4
	s_addc_u32 s7, s37, 0
	global_load_dwordx4 v[72:75], v4, s[6:7] offset:3072 nt
	v_readlane_b32 s8, v252, 38
	v_readlane_b32 s9, v252, 39
	s_lshl_b32 s10, s1, 7
	s_waitcnt vmcnt(0)
	ds_write_b128 v5, v[44:47]
	s_waitcnt lgkmcnt(0)
	s_barrier
	ds_read_u16 v22, v6
	ds_read_u16 v23, v6 offset:144
	ds_read_u16 v24, v6 offset:288
	ds_read_u16 v25, v6 offset:432
	ds_read_u16 v26, v6 offset:576
	ds_read_u16 v27, v6 offset:720
	ds_read_u16 v28, v6 offset:864
	ds_read_u16 v29, v6 offset:1008
	s_add_i32 s3, s0, 0
	s_lshl_b32 s3, s3, 20
	s_add_i32 s3, s3, s10
	s_add_u32 s6, s8, s3
	s_addc_u32 s7, s9, 0
	s_waitcnt lgkmcnt(0)
	v_lshl_or_b32 v76, v23, 16, v22
	v_lshl_or_b32 v77, v25, 16, v24
	v_lshl_or_b32 v78, v27, 16, v26
	v_lshl_or_b32 v79, v29, 16, v28
	global_store_dwordx4 v7, v[76:79], s[6:7]
	ds_write_b128 v5, v[48:51] offset:9216
	s_waitcnt lgkmcnt(0)
	s_barrier
	ds_read_u16 v22, v6 offset:9216
	ds_read_u16 v23, v6 offset:9360
	ds_read_u16 v24, v6 offset:9504
	ds_read_u16 v25, v6 offset:9648
	ds_read_u16 v26, v6 offset:9792
	ds_read_u16 v27, v6 offset:9936
	ds_read_u16 v28, v6 offset:10080
	ds_read_u16 v29, v6 offset:10224
	s_add_i32 s3, s0, 2
	s_lshl_b32 s3, s3, 20
	s_add_i32 s3, s3, s10
	s_add_u32 s6, s8, s3
	s_addc_u32 s7, s9, 0
	s_waitcnt lgkmcnt(0)
	v_lshl_or_b32 v80, v23, 16, v22
	v_lshl_or_b32 v81, v25, 16, v24
	v_lshl_or_b32 v82, v27, 16, v26
	v_lshl_or_b32 v83, v29, 16, v28
	global_store_dwordx4 v7, v[80:83], s[6:7]
	ds_write_b128 v5, v[52:55]
	s_waitcnt lgkmcnt(0)
	s_barrier
	ds_read_u16 v22, v6
	ds_read_u16 v23, v6 offset:144
	ds_read_u16 v24, v6 offset:288
	ds_read_u16 v25, v6 offset:432
	ds_read_u16 v26, v6 offset:576
	ds_read_u16 v27, v6 offset:720
	ds_read_u16 v28, v6 offset:864
	ds_read_u16 v29, v6 offset:1008
	s_add_i32 s3, s0, 4
	s_lshl_b32 s3, s3, 20
	s_add_i32 s3, s3, s10
	s_add_u32 s6, s8, s3
	s_addc_u32 s7, s9, 0
	s_waitcnt lgkmcnt(0)
	v_lshl_or_b32 v84, v23, 16, v22
	v_lshl_or_b32 v85, v25, 16, v24
	v_lshl_or_b32 v86, v27, 16, v26
	v_lshl_or_b32 v87, v29, 16, v28
	global_store_dwordx4 v7, v[84:87], s[6:7]
	ds_write_b128 v5, v[56:59] offset:9216
	s_waitcnt lgkmcnt(0)
	s_barrier
	ds_read_u16 v22, v6 offset:9216
	ds_read_u16 v23, v6 offset:9360
	ds_read_u16 v24, v6 offset:9504
	ds_read_u16 v25, v6 offset:9648
	ds_read_u16 v26, v6 offset:9792
	ds_read_u16 v27, v6 offset:9936
	ds_read_u16 v28, v6 offset:10080
	ds_read_u16 v29, v6 offset:10224
	s_add_i32 s3, s0, 6
	s_lshl_b32 s3, s3, 20
	s_add_i32 s3, s3, s10
	s_add_u32 s6, s8, s3
	s_addc_u32 s7, s9, 0
	s_waitcnt lgkmcnt(0)
	v_lshl_or_b32 v88, v23, 16, v22
	v_lshl_or_b32 v89, v25, 16, v24
	v_lshl_or_b32 v90, v27, 16, v26
	v_lshl_or_b32 v91, v29, 16, v28
	global_store_dwordx4 v7, v[88:91], s[6:7]
	ds_write_b128 v5, v[60:63]
	s_waitcnt lgkmcnt(0)
	s_barrier
	ds_read_u16 v22, v6
	ds_read_u16 v23, v6 offset:144
	ds_read_u16 v24, v6 offset:288
	ds_read_u16 v25, v6 offset:432
	ds_read_u16 v26, v6 offset:576
	ds_read_u16 v27, v6 offset:720
	ds_read_u16 v28, v6 offset:864
	ds_read_u16 v29, v6 offset:1008
	s_add_i32 s3, s0, 8
	s_lshl_b32 s3, s3, 20
	s_add_i32 s3, s3, s10
	s_add_u32 s6, s8, s3
	s_addc_u32 s7, s9, 0
	s_waitcnt lgkmcnt(0)
	v_lshl_or_b32 v92, v23, 16, v22
	v_lshl_or_b32 v93, v25, 16, v24
	v_lshl_or_b32 v94, v27, 16, v26
	v_lshl_or_b32 v95, v29, 16, v28
	global_store_dwordx4 v7, v[92:95], s[6:7]
	ds_write_b128 v5, v[64:67] offset:9216
	s_waitcnt lgkmcnt(0)
	s_barrier
	ds_read_u16 v22, v6 offset:9216
	ds_read_u16 v23, v6 offset:9360
	ds_read_u16 v24, v6 offset:9504
	ds_read_u16 v25, v6 offset:9648
	ds_read_u16 v26, v6 offset:9792
	ds_read_u16 v27, v6 offset:9936
	ds_read_u16 v28, v6 offset:10080
	ds_read_u16 v29, v6 offset:10224
	s_add_i32 s3, s0, 10
	s_lshl_b32 s3, s3, 20
	s_add_i32 s3, s3, s10
	s_add_u32 s6, s8, s3
	s_addc_u32 s7, s9, 0
	s_waitcnt lgkmcnt(0)
	v_lshl_or_b32 v96, v23, 16, v22
	v_lshl_or_b32 v97, v25, 16, v24
	v_lshl_or_b32 v98, v27, 16, v26
	v_lshl_or_b32 v99, v29, 16, v28
	global_store_dwordx4 v7, v[96:99], s[6:7]
	ds_write_b128 v5, v[68:71]
	s_waitcnt lgkmcnt(0)
	s_barrier
	ds_read_u16 v22, v6
	ds_read_u16 v23, v6 offset:144
	ds_read_u16 v24, v6 offset:288
	ds_read_u16 v25, v6 offset:432
	ds_read_u16 v26, v6 offset:576
	ds_read_u16 v27, v6 offset:720
	ds_read_u16 v28, v6 offset:864
	ds_read_u16 v29, v6 offset:1008
	s_add_i32 s3, s0, 12
	s_lshl_b32 s3, s3, 20
	s_add_i32 s3, s3, s10
	s_add_u32 s6, s8, s3
	s_addc_u32 s7, s9, 0
	s_waitcnt lgkmcnt(0)
	v_lshl_or_b32 v100, v23, 16, v22
	v_lshl_or_b32 v101, v25, 16, v24
	v_lshl_or_b32 v102, v27, 16, v26
	v_lshl_or_b32 v103, v29, 16, v28
	global_store_dwordx4 v7, v[100:103], s[6:7]
	ds_write_b128 v5, v[72:75] offset:9216
	s_waitcnt lgkmcnt(0)
	s_barrier
	ds_read_u16 v22, v6 offset:9216
	ds_read_u16 v23, v6 offset:9360
	ds_read_u16 v24, v6 offset:9504
	ds_read_u16 v25, v6 offset:9648
	ds_read_u16 v26, v6 offset:9792
	ds_read_u16 v27, v6 offset:9936
	ds_read_u16 v28, v6 offset:10080
	ds_read_u16 v29, v6 offset:10224
	s_add_i32 s3, s0, 14
	s_lshl_b32 s3, s3, 20
	s_add_i32 s3, s3, s10
	s_add_u32 s6, s8, s3
	s_addc_u32 s7, s9, 0
	s_waitcnt lgkmcnt(0)
	v_lshl_or_b32 v104, v23, 16, v22
	v_lshl_or_b32 v105, v25, 16, v24
	v_lshl_or_b32 v106, v27, 16, v26
	v_lshl_or_b32 v107, v29, 16, v28
	global_store_dwordx4 v7, v[104:107], s[6:7]

.LBB0_746:
	v_lshl_add_u32 v172, s84, 8, v180
	v_lshl_or_b32 v173, s83, 8, v182
	v_xor_b32_e32 v176, 16, v207
	v_xor_b32_e32 v177, 32, v207
	v_lshlrev_b32_e32 v175, 10, v172
	v_add_u32_e32 v175, v175, v173
	v_lshlrev_b32_e32 v174, 2, v175
	v_lshlrev_b32_e32 v175, 1, v175
	v_lshlrev_b32_e32 v173, 2, v173
	v_lshlrev_b32_e32 v172, 2, v172
	v_lshlrev_b32_e32 v176, 2, v176
	v_lshlrev_b32_e32 v177, 2, v177
	global_load_dwordx4 v[62:65], v173, s[4:5]
	global_load_dwordx4 v[58:61], v173, s[4:5] offset:16
	global_load_dwordx4 v[46:49], v173, s[4:5] offset:512
	global_load_dwordx4 v[34:37], v173, s[4:5] offset:528
	global_load_dwordx4 v[212:215], v174, s[2:3] nt
	global_load_dwordx4 v[216:219], v174, s[2:3] offset:16 nt
	global_load_dwordx4 v[220:223], v174, s[2:3] offset:512 nt
	global_load_dwordx4 v[224:227], v174, s[2:3] offset:528 nt
	s_add_u32 s86, s2, 0x10000
	s_addc_u32 s87, s3, 0
	global_load_dwordx4 v[228:231], v174, s[86:87] nt
	global_load_dwordx4 v[232:235], v174, s[86:87] offset:16 nt
	global_load_dwordx4 v[236:239], v174, s[86:87] offset:512 nt
	global_load_dwordx4 v[240:243], v174, s[86:87] offset:528 nt
	s_add_u32 s86, s2, 0x20000
	s_addc_u32 s87, s3, 0
	global_load_dwordx4 v[184:187], v174, s[86:87] nt
	global_load_dwordx4 v[188:191], v174, s[86:87] offset:16 nt
	global_load_dwordx4 v[192:195], v174, s[86:87] offset:512 nt
	global_load_dwordx4 v[244:247], v174, s[86:87] offset:528 nt
	s_lshl_b32 s13, s83, 2
	s_or_b32 s50, s13, s78
	s_ashr_i32 s51, s50, 31
	s_lshl_b64 s[50:51], s[50:51], 17
	v_readlane_b32 s60, v251, 55
	v_readlane_b32 s61, v251, 56
	s_nop 3
	s_add_u32 s50, s60, s50
	s_addc_u32 s51, s61, s51
	s_waitcnt vmcnt(0)
	v_pk_add_f32 v[142:143], v[142:143], v[212:213]
	v_pk_add_f32 v[144:145], v[144:145], v[214:215]
	v_pk_add_f32 v[138:139], v[138:139], v[216:217]
	v_pk_add_f32 v[140:141], v[140:141], v[218:219]
	v_pk_add_f32 v[134:135], v[134:135], v[220:221]
	v_pk_add_f32 v[136:137], v[136:137], v[222:223]
	v_pk_add_f32 v[130:131], v[130:131], v[224:225]
	v_pk_add_f32 v[132:133], v[132:133], v[226:227]
	global_store_dwordx4 v174, v[142:145], s[16:17]
	global_store_dwordx4 v174, v[138:141], s[16:17] offset:16
	global_store_dwordx4 v174, v[134:137], s[16:17] offset:512
	global_store_dwordx4 v174, v[130:133], s[16:17] offset:528
	v_mul_f32_e32 v149, v145, v145
	v_mul_f32_e32 v148, v143, v143
	v_fmac_f32_e32 v148, v142, v142
	v_fmac_f32_e32 v149, v144, v144
	v_add_f32_e32 v148, v148, v149
	v_mul_f32_e32 v149, v139, v139
	v_fmac_f32_e32 v149, v138, v138
	v_add_f32_e32 v148, v148, v149
	v_mul_f32_e32 v149, v141, v141
	v_fmac_f32_e32 v149, v140, v140
	v_add_f32_e32 v178, v149, v148
	v_mul_f32_e32 v149, v137, v137
	v_mul_f32_e32 v148, v135, v135
	v_fmac_f32_e32 v148, v134, v134
	v_fmac_f32_e32 v149, v136, v136
	v_add_f32_e32 v148, v148, v149
	v_mul_f32_e32 v149, v131, v131
	v_fmac_f32_e32 v149, v130, v130
	v_add_f32_e32 v148, v148, v149
	v_mul_f32_e32 v149, v133, v133
	v_fmac_f32_e32 v149, v132, v132
	v_add_f32_e32 v148, v149, v148
	v_add_f32_e32 v178, v178, v148
	ds_bpermute_b32 v179, v176, v178
	v_pk_mul_f32 v[212:213], v[62:63], v[142:143]
	v_pk_mul_f32 v[214:215], v[64:65], v[144:145]
	v_pk_mul_f32 v[216:217], v[58:59], v[138:139]
	v_pk_mul_f32 v[218:219], v[60:61], v[140:141]
	v_pk_mul_f32 v[220:221], v[46:47], v[134:135]
	v_pk_mul_f32 v[222:223], v[48:49], v[136:137]
	v_pk_mul_f32 v[224:225], v[34:35], v[130:131]
	v_pk_mul_f32 v[226:227], v[36:37], v[132:133]
	s_waitcnt lgkmcnt(0)
	v_add_f32_e32 v178, v178, v179
	ds_bpermute_b32 v248, v177, v178
	v_cvt_pk_bf16_f32 v212, v212, v213
	v_cvt_pk_bf16_f32 v213, v214, v215
	v_cvt_pk_bf16_f32 v214, v216, v217
	v_cvt_pk_bf16_f32 v215, v218, v219
	v_cvt_pk_bf16_f32 v220, v220, v221
	v_cvt_pk_bf16_f32 v221, v222, v223
	v_cvt_pk_bf16_f32 v222, v224, v225
	v_cvt_pk_bf16_f32 v223, v226, v227
	global_store_dwordx4 v175, v[212:215], s[34:35]
	global_store_dwordx4 v175, v[220:223], s[34:35] offset:256
	s_waitcnt lgkmcnt(0)
	v_add_f32_e32 v178, v178, v248
	s_and_saveexec_b64 s[58:59], s[40:41]
	global_store_dword v172, v178, s[50:51]
	s_or_b64 exec, exec, s[58:59]
	v_pk_add_f32 v[126:127], v[126:127], v[228:229]
	v_pk_add_f32 v[128:129], v[128:129], v[230:231]
	v_pk_add_f32 v[122:123], v[122:123], v[232:233]
	v_pk_add_f32 v[124:125], v[124:125], v[234:235]
	v_pk_add_f32 v[118:119], v[118:119], v[236:237]
	v_pk_add_f32 v[120:121], v[120:121], v[238:239]
	v_pk_add_f32 v[114:115], v[114:115], v[240:241]
	v_pk_add_f32 v[116:117], v[116:117], v[242:243]
	s_add_u32 s88, s16, 0x10000
	s_addc_u32 s89, s17, 0
	s_add_u32 s90, s34, 0x8000
	s_addc_u32 s91, s35, 0
	global_store_dwordx4 v174, v[126:129], s[88:89]
	global_store_dwordx4 v174, v[122:125], s[88:89] offset:16
	global_store_dwordx4 v174, v[118:121], s[88:89] offset:512
	global_store_dwordx4 v174, v[114:117], s[88:89] offset:528
	v_mul_f32_e32 v149, v129, v129
	v_mul_f32_e32 v148, v127, v127
	v_fmac_f32_e32 v148, v126, v126
	v_fmac_f32_e32 v149, v128, v128
	v_add_f32_e32 v148, v148, v149
	v_mul_f32_e32 v149, v123, v123
	v_fmac_f32_e32 v149, v122, v122
	v_add_f32_e32 v148, v148, v149
	v_mul_f32_e32 v149, v125, v125
	v_fmac_f32_e32 v149, v124, v124
	v_add_f32_e32 v178, v149, v148
	v_mul_f32_e32 v149, v121, v121
	v_mul_f32_e32 v148, v119, v119
	v_fmac_f32_e32 v148, v118, v118
	v_fmac_f32_e32 v149, v120, v120
	v_add_f32_e32 v148, v148, v149
	v_mul_f32_e32 v149, v115, v115
	v_fmac_f32_e32 v149, v114, v114
	v_add_f32_e32 v148, v148, v149
	v_mul_f32_e32 v149, v117, v117
	v_fmac_f32_e32 v149, v116, v116
	v_add_f32_e32 v148, v149, v148
	v_add_f32_e32 v178, v178, v148
	ds_bpermute_b32 v179, v176, v178
	v_pk_mul_f32 v[228:229], v[62:63], v[126:127]
	v_pk_mul_f32 v[230:231], v[64:65], v[128:129]
	v_pk_mul_f32 v[232:233], v[58:59], v[122:123]
	v_pk_mul_f32 v[234:235], v[60:61], v[124:125]
	v_pk_mul_f32 v[236:237], v[46:47], v[118:119]
	v_pk_mul_f32 v[238:239], v[48:49], v[120:121]
	v_pk_mul_f32 v[240:241], v[34:35], v[114:115]
	v_pk_mul_f32 v[242:243], v[36:37], v[116:117]
	s_waitcnt lgkmcnt(0)
	v_add_f32_e32 v178, v178, v179
	ds_bpermute_b32 v248, v177, v178
	v_cvt_pk_bf16_f32 v228, v228, v229
	v_cvt_pk_bf16_f32 v229, v230, v231
	v_cvt_pk_bf16_f32 v230, v232, v233
	v_cvt_pk_bf16_f32 v231, v234, v235
	v_cvt_pk_bf16_f32 v236, v236, v237
	v_cvt_pk_bf16_f32 v237, v238, v239
	v_cvt_pk_bf16_f32 v238, v240, v241
	v_cvt_pk_bf16_f32 v239, v242, v243
	global_store_dwordx4 v175, v[228:231], s[90:91]
	global_store_dwordx4 v175, v[236:239], s[90:91] offset:256
	s_waitcnt lgkmcnt(0)
	v_add_f32_e32 v178, v178, v248
	s_and_saveexec_b64 s[58:59], s[40:41]
	global_store_dword v172, v178, s[50:51] offset:64
	s_or_b64 exec, exec, s[58:59]
	v_pk_add_f32 v[110:111], v[110:111], v[184:185]
	v_pk_add_f32 v[112:113], v[112:113], v[186:187]
	v_pk_add_f32 v[106:107], v[106:107], v[188:189]
	v_pk_add_f32 v[108:109], v[108:109], v[190:191]
	v_pk_add_f32 v[102:103], v[102:103], v[192:193]
	v_pk_add_f32 v[104:105], v[104:105], v[194:195]
	v_pk_add_f32 v[98:99], v[98:99], v[244:245]
	v_pk_add_f32 v[100:101], v[100:101], v[246:247]
	s_add_u32 s88, s16, 0x20000
	s_addc_u32 s89, s17, 0
	s_add_u32 s90, s34, 0x10000
	s_addc_u32 s91, s35, 0
	global_store_dwordx4 v174, v[110:113], s[88:89]
	global_store_dwordx4 v174, v[106:109], s[88:89] offset:16
	global_store_dwordx4 v174, v[102:105], s[88:89] offset:512
	global_store_dwordx4 v174, v[98:101], s[88:89] offset:528
	v_mul_f32_e32 v149, v113, v113
	v_mul_f32_e32 v148, v111, v111
	v_fmac_f32_e32 v148, v110, v110
	v_fmac_f32_e32 v149, v112, v112
	v_add_f32_e32 v148, v148, v149
	v_mul_f32_e32 v149, v107, v107
	v_fmac_f32_e32 v149, v106, v106
	v_add_f32_e32 v148, v148, v149
	v_mul_f32_e32 v149, v109, v109
	v_fmac_f32_e32 v149, v108, v108
	v_add_f32_e32 v178, v149, v148
	v_mul_f32_e32 v149, v105, v105
	v_mul_f32_e32 v148, v103, v103
	v_fmac_f32_e32 v148, v102, v102
	v_fmac_f32_e32 v149, v104, v104
	v_add_f32_e32 v148, v148, v149
	v_mul_f32_e32 v149, v99, v99
	v_fmac_f32_e32 v149, v98, v98
	v_add_f32_e32 v148, v148, v149
	v_mul_f32_e32 v149, v101, v101
	v_fmac_f32_e32 v149, v100, v100
	v_add_f32_e32 v148, v149, v148
	v_add_f32_e32 v178, v178, v148
	ds_bpermute_b32 v179, v176, v178
	v_pk_mul_f32 v[184:185], v[62:63], v[110:111]
	v_pk_mul_f32 v[186:187], v[64:65], v[112:113]
	v_pk_mul_f32 v[188:189], v[58:59], v[106:107]
	v_pk_mul_f32 v[190:191], v[60:61], v[108:109]
	v_pk_mul_f32 v[192:193], v[46:47], v[102:103]
	v_pk_mul_f32 v[194:195], v[48:49], v[104:105]
	v_pk_mul_f32 v[244:245], v[34:35], v[98:99]
	v_pk_mul_f32 v[246:247], v[36:37], v[100:101]
	s_waitcnt lgkmcnt(0)
	v_add_f32_e32 v178, v178, v179
	ds_bpermute_b32 v248, v177, v178
	v_cvt_pk_bf16_f32 v184, v184, v185
	v_cvt_pk_bf16_f32 v185, v186, v187
	v_cvt_pk_bf16_f32 v186, v188, v189
	v_cvt_pk_bf16_f32 v187, v190, v191
	v_cvt_pk_bf16_f32 v192, v192, v193
	v_cvt_pk_bf16_f32 v193, v194, v195
	v_cvt_pk_bf16_f32 v194, v244, v245
	v_cvt_pk_bf16_f32 v195, v246, v247
	global_store_dwordx4 v175, v[184:187], s[90:91]
	global_store_dwordx4 v175, v[192:195], s[90:91] offset:256
	s_waitcnt lgkmcnt(0)
	v_add_f32_e32 v178, v178, v248
	s_and_saveexec_b64 s[58:59], s[40:41]
	global_store_dword v172, v178, s[50:51] offset:128
	s_or_b64 exec, exec, s[58:59]
	s_add_u32 s86, s2, 0x30000
	s_addc_u32 s87, s3, 0
	global_load_dwordx4 v[212:215], v174, s[86:87] nt
	global_load_dwordx4 v[216:219], v174, s[86:87] offset:16 nt
	global_load_dwordx4 v[220:223], v174, s[86:87] offset:512 nt
	global_load_dwordx4 v[224:227], v174, s[86:87] offset:528 nt
	s_add_u32 s86, s2, 0x80000
	s_addc_u32 s87, s3, 0
	global_load_dwordx4 v[228:231], v174, s[86:87] nt
	global_load_dwordx4 v[232:235], v174, s[86:87] offset:16 nt
	global_load_dwordx4 v[236:239], v174, s[86:87] offset:512 nt
	global_load_dwordx4 v[240:243], v174, s[86:87] offset:528 nt
	s_add_u32 s86, s2, 0x90000
	s_addc_u32 s87, s3, 0
	global_load_dwordx4 v[184:187], v174, s[86:87] nt
	global_load_dwordx4 v[188:191], v174, s[86:87] offset:16 nt
	global_load_dwordx4 v[192:195], v174, s[86:87] offset:512 nt
	global_load_dwordx4 v[244:247], v174, s[86:87] offset:528 nt
	s_waitcnt vmcnt(0)
	v_pk_add_f32 v[94:95], v[94:95], v[212:213]
	v_pk_add_f32 v[96:97], v[96:97], v[214:215]
	v_pk_add_f32 v[90:91], v[90:91], v[216:217]
	v_pk_add_f32 v[92:93], v[92:93], v[218:219]
	v_pk_add_f32 v[86:87], v[86:87], v[220:221]
	v_pk_add_f32 v[88:89], v[88:89], v[222:223]
	v_pk_add_f32 v[82:83], v[82:83], v[224:225]
	v_pk_add_f32 v[84:85], v[84:85], v[226:227]
	s_add_u32 s88, s16, 0x30000
	s_addc_u32 s89, s17, 0
	s_add_u32 s90, s34, 0x18000
	s_addc_u32 s91, s35, 0
	global_store_dwordx4 v174, v[94:97], s[88:89]
	global_store_dwordx4 v174, v[90:93], s[88:89] offset:16
	global_store_dwordx4 v174, v[86:89], s[88:89] offset:512
	global_store_dwordx4 v174, v[82:85], s[88:89] offset:528
	v_mul_f32_e32 v149, v97, v97
	v_mul_f32_e32 v148, v95, v95
	v_fmac_f32_e32 v148, v94, v94
	v_fmac_f32_e32 v149, v96, v96
	v_add_f32_e32 v148, v148, v149
	v_mul_f32_e32 v149, v91, v91
	v_fmac_f32_e32 v149, v90, v90
	v_add_f32_e32 v148, v148, v149
	v_mul_f32_e32 v149, v93, v93
	v_fmac_f32_e32 v149, v92, v92
	v_add_f32_e32 v178, v149, v148
	v_mul_f32_e32 v149, v89, v89
	v_mul_f32_e32 v148, v87, v87
	v_fmac_f32_e32 v148, v86, v86
	v_fmac_f32_e32 v149, v88, v88
	v_add_f32_e32 v148, v148, v149
	v_mul_f32_e32 v149, v83, v83
	v_fmac_f32_e32 v149, v82, v82
	v_add_f32_e32 v148, v148, v149
	v_mul_f32_e32 v149, v85, v85
	v_fmac_f32_e32 v149, v84, v84
	v_add_f32_e32 v148, v149, v148
	v_add_f32_e32 v178, v178, v148
	ds_bpermute_b32 v179, v176, v178
	v_pk_mul_f32 v[212:213], v[62:63], v[94:95]
	v_pk_mul_f32 v[214:215], v[64:65], v[96:97]
	v_pk_mul_f32 v[216:217], v[58:59], v[90:91]
	v_pk_mul_f32 v[218:219], v[60:61], v[92:93]
	v_pk_mul_f32 v[220:221], v[46:47], v[86:87]
	v_pk_mul_f32 v[222:223], v[48:49], v[88:89]
	v_pk_mul_f32 v[224:225], v[34:35], v[82:83]
	v_pk_mul_f32 v[226:227], v[36:37], v[84:85]
	s_waitcnt lgkmcnt(0)
	v_add_f32_e32 v178, v178, v179
	ds_bpermute_b32 v248, v177, v178
	v_cvt_pk_bf16_f32 v212, v212, v213
	v_cvt_pk_bf16_f32 v213, v214, v215
	v_cvt_pk_bf16_f32 v214, v216, v217
	v_cvt_pk_bf16_f32 v215, v218, v219
	v_cvt_pk_bf16_f32 v220, v220, v221
	v_cvt_pk_bf16_f32 v221, v222, v223
	v_cvt_pk_bf16_f32 v222, v224, v225
	v_cvt_pk_bf16_f32 v223, v226, v227
	global_store_dwordx4 v175, v[212:215], s[90:91]
	global_store_dwordx4 v175, v[220:223], s[90:91] offset:256
	s_waitcnt lgkmcnt(0)
	v_add_f32_e32 v178, v178, v248
	s_and_saveexec_b64 s[58:59], s[40:41]
	global_store_dword v172, v178, s[50:51] offset:192
	s_or_b64 exec, exec, s[58:59]
	v_pk_add_f32 v[78:79], v[78:79], v[228:229]
	v_pk_add_f32 v[80:81], v[80:81], v[230:231]
	v_pk_add_f32 v[74:75], v[74:75], v[232:233]
	v_pk_add_f32 v[76:77], v[76:77], v[234:235]
	v_pk_add_f32 v[70:71], v[70:71], v[236:237]
	v_pk_add_f32 v[72:73], v[72:73], v[238:239]
	v_pk_add_f32 v[66:67], v[66:67], v[240:241]
	v_pk_add_f32 v[68:69], v[68:69], v[242:243]
	s_add_u32 s88, s16, 0x80000
	s_addc_u32 s89, s17, 0
	s_add_u32 s90, s34, 0x40000
	s_addc_u32 s91, s35, 0
	global_store_dwordx4 v174, v[78:81], s[88:89]
	global_store_dwordx4 v174, v[74:77], s[88:89] offset:16
	global_store_dwordx4 v174, v[70:73], s[88:89] offset:512
	global_store_dwordx4 v174, v[66:69], s[88:89] offset:528
	v_mul_f32_e32 v149, v81, v81
	v_mul_f32_e32 v148, v79, v79
	v_fmac_f32_e32 v148, v78, v78
	v_fmac_f32_e32 v149, v80, v80
	v_add_f32_e32 v148, v148, v149
	v_mul_f32_e32 v149, v75, v75
	v_fmac_f32_e32 v149, v74, v74
	v_add_f32_e32 v148, v148, v149
	v_mul_f32_e32 v149, v77, v77
	v_fmac_f32_e32 v149, v76, v76
	v_add_f32_e32 v178, v149, v148
	v_mul_f32_e32 v149, v73, v73
	v_mul_f32_e32 v148, v71, v71
	v_fmac_f32_e32 v148, v70, v70
	v_fmac_f32_e32 v149, v72, v72
	v_add_f32_e32 v148, v148, v149
	v_mul_f32_e32 v149, v67, v67
	v_fmac_f32_e32 v149, v66, v66
	v_add_f32_e32 v148, v148, v149
	v_mul_f32_e32 v149, v69, v69
	v_fmac_f32_e32 v149, v68, v68
	v_add_f32_e32 v148, v149, v148
	v_add_f32_e32 v178, v178, v148
	ds_bpermute_b32 v179, v176, v178
	v_pk_mul_f32 v[228:229], v[62:63], v[78:79]
	v_pk_mul_f32 v[230:231], v[64:65], v[80:81]
	v_pk_mul_f32 v[232:233], v[58:59], v[74:75]
	v_pk_mul_f32 v[234:235], v[60:61], v[76:77]
	v_pk_mul_f32 v[236:237], v[46:47], v[70:71]
	v_pk_mul_f32 v[238:239], v[48:49], v[72:73]
	v_pk_mul_f32 v[240:241], v[34:35], v[66:67]
	v_pk_mul_f32 v[242:243], v[36:37], v[68:69]
	s_waitcnt lgkmcnt(0)
	v_add_f32_e32 v178, v178, v179
	ds_bpermute_b32 v248, v177, v178
	v_cvt_pk_bf16_f32 v228, v228, v229
	v_cvt_pk_bf16_f32 v229, v230, v231
	v_cvt_pk_bf16_f32 v230, v232, v233
	v_cvt_pk_bf16_f32 v231, v234, v235
	v_cvt_pk_bf16_f32 v236, v236, v237
	v_cvt_pk_bf16_f32 v237, v238, v239
	v_cvt_pk_bf16_f32 v238, v240, v241
	v_cvt_pk_bf16_f32 v239, v242, v243
	global_store_dwordx4 v175, v[228:231], s[90:91]
	global_store_dwordx4 v175, v[236:239], s[90:91] offset:256
	s_waitcnt lgkmcnt(0)
	v_add_f32_e32 v178, v178, v248
	s_and_saveexec_b64 s[58:59], s[40:41]
	global_store_dword v172, v178, s[50:51] offset:512
	s_or_b64 exec, exec, s[58:59]
	v_pk_add_f32 v[54:55], v[54:55], v[184:185]
	v_pk_add_f32 v[56:57], v[56:57], v[186:187]
	v_pk_add_f32 v[50:51], v[50:51], v[188:189]
	v_pk_add_f32 v[52:53], v[52:53], v[190:191]
	v_pk_add_f32 v[42:43], v[42:43], v[192:193]
	v_pk_add_f32 v[44:45], v[44:45], v[194:195]
	v_pk_add_f32 v[38:39], v[38:39], v[244:245]
	v_pk_add_f32 v[40:41], v[40:41], v[246:247]
	s_add_u32 s88, s16, 0x90000
	s_addc_u32 s89, s17, 0
	s_add_u32 s90, s34, 0x48000
	s_addc_u32 s91, s35, 0
	global_store_dwordx4 v174, v[54:57], s[88:89]
	global_store_dwordx4 v174, v[50:53], s[88:89] offset:16
	global_store_dwordx4 v174, v[42:45], s[88:89] offset:512
	global_store_dwordx4 v174, v[38:41], s[88:89] offset:528
	v_mul_f32_e32 v149, v57, v57
	v_mul_f32_e32 v148, v55, v55
	v_fmac_f32_e32 v148, v54, v54
	v_fmac_f32_e32 v149, v56, v56
	v_add_f32_e32 v148, v148, v149
	v_mul_f32_e32 v149, v51, v51
	v_fmac_f32_e32 v149, v50, v50
	v_add_f32_e32 v148, v148, v149
	v_mul_f32_e32 v149, v53, v53
	v_fmac_f32_e32 v149, v52, v52
	v_add_f32_e32 v178, v149, v148
	v_mul_f32_e32 v149, v45, v45
	v_mul_f32_e32 v148, v43, v43
	v_fmac_f32_e32 v148, v42, v42
	v_fmac_f32_e32 v149, v44, v44
	v_add_f32_e32 v148, v148, v149
	v_mul_f32_e32 v149, v39, v39
	v_fmac_f32_e32 v149, v38, v38
	v_add_f32_e32 v148, v148, v149
	v_mul_f32_e32 v149, v41, v41
	v_fmac_f32_e32 v149, v40, v40
	v_add_f32_e32 v148, v149, v148
	v_add_f32_e32 v178, v178, v148
	ds_bpermute_b32 v179, v176, v178
	v_pk_mul_f32 v[184:185], v[62:63], v[54:55]
	v_pk_mul_f32 v[186:187], v[64:65], v[56:57]
	v_pk_mul_f32 v[188:189], v[58:59], v[50:51]
	v_pk_mul_f32 v[190:191], v[60:61], v[52:53]
	v_pk_mul_f32 v[192:193], v[46:47], v[42:43]
	v_pk_mul_f32 v[194:195], v[48:49], v[44:45]
	v_pk_mul_f32 v[244:245], v[34:35], v[38:39]
	v_pk_mul_f32 v[246:247], v[36:37], v[40:41]
	s_waitcnt lgkmcnt(0)
	v_add_f32_e32 v178, v178, v179
	ds_bpermute_b32 v248, v177, v178
	v_cvt_pk_bf16_f32 v184, v184, v185
	v_cvt_pk_bf16_f32 v185, v186, v187
	v_cvt_pk_bf16_f32 v186, v188, v189
	v_cvt_pk_bf16_f32 v187, v190, v191
	v_cvt_pk_bf16_f32 v192, v192, v193
	v_cvt_pk_bf16_f32 v193, v194, v195
	v_cvt_pk_bf16_f32 v194, v244, v245
	v_cvt_pk_bf16_f32 v195, v246, v247
	global_store_dwordx4 v175, v[184:187], s[90:91]
	global_store_dwordx4 v175, v[192:195], s[90:91] offset:256
	s_waitcnt lgkmcnt(0)
	v_add_f32_e32 v178, v178, v248
	s_and_saveexec_b64 s[58:59], s[40:41]
	global_store_dword v172, v178, s[50:51] offset:576
	s_or_b64 exec, exec, s[58:59]
	s_add_u32 s86, s2, 0xa0000
	s_addc_u32 s87, s3, 0
	global_load_dwordx4 v[212:215], v174, s[86:87] nt
	global_load_dwordx4 v[216:219], v174, s[86:87] offset:16 nt
	global_load_dwordx4 v[220:223], v174, s[86:87] offset:512 nt
	global_load_dwordx4 v[224:227], v174, s[86:87] offset:528 nt
	s_add_u32 s86, s2, 0xb0000
	s_addc_u32 s87, s3, 0
	global_load_dwordx4 v[228:231], v174, s[86:87] nt
	global_load_dwordx4 v[232:235], v174, s[86:87] offset:16 nt
	global_load_dwordx4 v[236:239], v174, s[86:87] offset:512 nt
	global_load_dwordx4 v[240:243], v174, s[86:87] offset:528 nt
	s_waitcnt vmcnt(0)
	v_pk_add_f32 v[30:31], v[30:31], v[212:213]
	v_pk_add_f32 v[32:33], v[32:33], v[214:215]
	v_pk_add_f32 v[26:27], v[26:27], v[216:217]
	v_pk_add_f32 v[28:29], v[28:29], v[218:219]
	v_pk_add_f32 v[22:23], v[22:23], v[220:221]
	v_pk_add_f32 v[24:25], v[24:25], v[222:223]
	v_pk_add_f32 v[18:19], v[18:19], v[224:225]
	v_pk_add_f32 v[20:21], v[20:21], v[226:227]
	s_add_u32 s88, s16, 0xa0000
	s_addc_u32 s89, s17, 0
	s_add_u32 s90, s34, 0x50000
	s_addc_u32 s91, s35, 0
	global_store_dwordx4 v174, v[30:33], s[88:89]
	global_store_dwordx4 v174, v[26:29], s[88:89] offset:16
	global_store_dwordx4 v174, v[22:25], s[88:89] offset:512
	global_store_dwordx4 v174, v[18:21], s[88:89] offset:528
	v_mul_f32_e32 v149, v33, v33
	v_mul_f32_e32 v148, v31, v31
	v_fmac_f32_e32 v148, v30, v30
	v_fmac_f32_e32 v149, v32, v32
	v_add_f32_e32 v148, v148, v149
	v_mul_f32_e32 v149, v27, v27
	v_fmac_f32_e32 v149, v26, v26
	v_add_f32_e32 v148, v148, v149
	v_mul_f32_e32 v149, v29, v29
	v_fmac_f32_e32 v149, v28, v28
	v_add_f32_e32 v178, v149, v148
	v_mul_f32_e32 v149, v25, v25
	v_mul_f32_e32 v148, v23, v23
	v_fmac_f32_e32 v148, v22, v22
	v_fmac_f32_e32 v149, v24, v24
	v_add_f32_e32 v148, v148, v149
	v_mul_f32_e32 v149, v19, v19
	v_fmac_f32_e32 v149, v18, v18
	v_add_f32_e32 v148, v148, v149
	v_mul_f32_e32 v149, v21, v21
	v_fmac_f32_e32 v149, v20, v20
	v_add_f32_e32 v148, v149, v148
	v_add_f32_e32 v178, v178, v148
	ds_bpermute_b32 v179, v176, v178
	v_pk_mul_f32 v[212:213], v[62:63], v[30:31]
	v_pk_mul_f32 v[214:215], v[64:65], v[32:33]
	v_pk_mul_f32 v[216:217], v[58:59], v[26:27]
	v_pk_mul_f32 v[218:219], v[60:61], v[28:29]
	v_pk_mul_f32 v[220:221], v[46:47], v[22:23]
	v_pk_mul_f32 v[222:223], v[48:49], v[24:25]
	v_pk_mul_f32 v[224:225], v[34:35], v[18:19]
	v_pk_mul_f32 v[226:227], v[36:37], v[20:21]
	s_waitcnt lgkmcnt(0)
	v_add_f32_e32 v178, v178, v179
	ds_bpermute_b32 v248, v177, v178
	v_cvt_pk_bf16_f32 v212, v212, v213
	v_cvt_pk_bf16_f32 v213, v214, v215
	v_cvt_pk_bf16_f32 v214, v216, v217
	v_cvt_pk_bf16_f32 v215, v218, v219
	v_cvt_pk_bf16_f32 v220, v220, v221
	v_cvt_pk_bf16_f32 v221, v222, v223
	v_cvt_pk_bf16_f32 v222, v224, v225
	v_cvt_pk_bf16_f32 v223, v226, v227
	global_store_dwordx4 v175, v[212:215], s[90:91]
	global_store_dwordx4 v175, v[220:223], s[90:91] offset:256
	s_waitcnt lgkmcnt(0)
	v_add_f32_e32 v178, v178, v248
	s_and_saveexec_b64 s[58:59], s[40:41]
	global_store_dword v172, v178, s[50:51] offset:640
	s_or_b64 exec, exec, s[58:59]
	v_pk_add_f32 v[14:15], v[14:15], v[228:229]
	v_pk_add_f32 v[16:17], v[16:17], v[230:231]
	v_pk_add_f32 v[10:11], v[10:11], v[232:233]
	v_pk_add_f32 v[12:13], v[12:13], v[234:235]
	v_pk_add_f32 v[6:7], v[6:7], v[236:237]
	v_pk_add_f32 v[8:9], v[8:9], v[238:239]
	v_pk_add_f32 v[2:3], v[2:3], v[240:241]
	v_pk_add_f32 v[4:5], v[4:5], v[242:243]
	s_add_u32 s88, s16, 0xb0000
	s_addc_u32 s89, s17, 0
	s_add_u32 s90, s34, 0x58000
	s_addc_u32 s91, s35, 0
	global_store_dwordx4 v174, v[14:17], s[88:89]
	global_store_dwordx4 v174, v[10:13], s[88:89] offset:16
	global_store_dwordx4 v174, v[6:9], s[88:89] offset:512
	global_store_dwordx4 v174, v[2:5], s[88:89] offset:528
	v_mul_f32_e32 v149, v17, v17
	v_mul_f32_e32 v148, v15, v15
	v_fmac_f32_e32 v148, v14, v14
	v_fmac_f32_e32 v149, v16, v16
	v_add_f32_e32 v148, v148, v149
	v_mul_f32_e32 v149, v11, v11
	v_fmac_f32_e32 v149, v10, v10
	v_add_f32_e32 v148, v148, v149
	v_mul_f32_e32 v149, v13, v13
	v_fmac_f32_e32 v149, v12, v12
	v_add_f32_e32 v178, v149, v148
	v_mul_f32_e32 v149, v9, v9
	v_mul_f32_e32 v148, v7, v7
	v_fmac_f32_e32 v148, v6, v6
	v_fmac_f32_e32 v149, v8, v8
	v_add_f32_e32 v148, v148, v149
	v_mul_f32_e32 v149, v3, v3
	v_fmac_f32_e32 v149, v2, v2
	v_add_f32_e32 v148, v148, v149
	v_mul_f32_e32 v149, v5, v5
	v_fmac_f32_e32 v149, v4, v4
	v_add_f32_e32 v148, v149, v148
	v_add_f32_e32 v178, v178, v148
	ds_bpermute_b32 v179, v176, v178
	v_pk_mul_f32 v[228:229], v[62:63], v[14:15]
	v_pk_mul_f32 v[230:231], v[64:65], v[16:17]
	v_pk_mul_f32 v[232:233], v[58:59], v[10:11]
	v_pk_mul_f32 v[234:235], v[60:61], v[12:13]
	v_pk_mul_f32 v[236:237], v[46:47], v[6:7]
	v_pk_mul_f32 v[238:239], v[48:49], v[8:9]
	v_pk_mul_f32 v[240:241], v[34:35], v[2:3]
	v_pk_mul_f32 v[242:243], v[36:37], v[4:5]
	s_waitcnt lgkmcnt(0)
	v_add_f32_e32 v178, v178, v179
	ds_bpermute_b32 v248, v177, v178
	v_cvt_pk_bf16_f32 v228, v228, v229
	v_cvt_pk_bf16_f32 v229, v230, v231
	v_cvt_pk_bf16_f32 v230, v232, v233
	v_cvt_pk_bf16_f32 v231, v234, v235
	v_cvt_pk_bf16_f32 v236, v236, v237
	v_cvt_pk_bf16_f32 v237, v238, v239
	v_cvt_pk_bf16_f32 v238, v240, v241
	v_cvt_pk_bf16_f32 v239, v242, v243
	global_store_dwordx4 v175, v[228:231], s[90:91]
	global_store_dwordx4 v175, v[236:239], s[90:91] offset:256
	s_waitcnt lgkmcnt(0)
	v_add_f32_e32 v178, v178, v248
	s_and_saveexec_b64 s[58:59], s[40:41]
	global_store_dword v172, v178, s[50:51] offset:704
	s_or_b64 exec, exec, s[58:59]
	s_andn2_b64 vcc, exec, s[42:43]
	s_mov_b64 s[42:43], -1
	s_cbranch_vccnz .LBB0_734
	s_andn2_b64 vcc, exec, s[0:1]
	s_cbranch_vccnz .LBB0_733
	s_barrier
	s_branch .LBB0_733
